# hand-written RWKV-7 recurrence inner loops (16 steps unrolled, immediate LDS offsets, shorter dependency chain, rows 2q/2q+1 per lane)
# speedup vs baseline: 1.0507x; 1.0235x over previous
.LBB0_144:
	s_or_saveexec_b64 s[12:13], s[42:43]
	s_mul_i32 s45, s45, 0xc000
	v_cndmask_b32_e64 v8, 0, 1, s[40:41]
	s_add_i32 s42, s45, 0
	v_mul_lo_u32 v73, v8, s47
	v_add_u32_e32 v69, s42, v92
	v_lshl_add_u32 v100, v59, 2, s42
	s_xor_b64 exec, exec, s[12:13]
	s_cbranch_execz .LBB0_148
	v_bfe_u32 v119, v171, 4, 2
	v_lshl_add_u32 v118, v119, 2, v100
	v_lshl_add_u32 v119, v119, 6, v94
	v_add_u32_e32 v119, 0x18000, v119
	ds_read_b128 v[12:15], v69 offset:256
	ds_read_b128 v[20:23], v69 offset:768
	ds_read_b64 v[28:29], v118 offset:1280
	ds_read_b128 v[8:11], v69 offset:0
	ds_read_b128 v[16:19], v69 offset:512
	ds_read_b128 v[24:27], v69 offset:1024
	s_setprio 3
	s_waitcnt lgkmcnt(0)
	v_pk_mul_f32 v[110:111], v[2:3], v[14:15]
	v_pk_mul_f32 v[112:113], v[6:7], v[14:15]
	v_pk_fma_f32 v[110:111], v[0:1], v[12:13], v[110:111]
	v_pk_fma_f32 v[112:113], v[4:5], v[12:13], v[112:113]
	ds_read_b128 v[34:37], v69 offset:1792
	ds_read_b128 v[78:81], v69 offset:2304
	ds_read_b64 v[108:109], v118 offset:2816
	ds_read_b128 v[30:33], v69 offset:1536
	ds_read_b128 v[74:77], v69 offset:2048
	ds_read_b128 v[104:107], v69 offset:2560
	v_add_f32_e32 v70, v110, v111
	v_add_f32_e32 v72, v112, v113
	v_pk_mul_f32 v[38:39], v[20:21], v[28:29] op_sel_hi:[1,0]
	v_add_f32_dpp v70, v70, v70 row_ror:8 row_mask:0xf bank_mask:0xf bound_ctrl:1
	v_add_f32_dpp v72, v72, v72 row_ror:8 row_mask:0xf bank_mask:0xf bound_ctrl:1
	v_pk_mul_f32 v[82:83], v[22:23], v[28:29] op_sel_hi:[1,0]
	v_add_f32_dpp v70, v70, v70 row_ror:4 row_mask:0xf bank_mask:0xf bound_ctrl:1
	v_add_f32_dpp v72, v72, v72 row_ror:4 row_mask:0xf bank_mask:0xf bound_ctrl:1
	v_pk_mul_f32 v[116:117], v[20:21], v[28:29] op_sel:[0,1] op_sel_hi:[1,1]
	v_add_f32_dpp v70, v70, v70 row_ror:2 row_mask:0xf bank_mask:0xf bound_ctrl:1
	v_add_f32_dpp v72, v72, v72 row_ror:2 row_mask:0xf bank_mask:0xf bound_ctrl:1
	v_pk_mul_f32 v[114:115], v[22:23], v[28:29] op_sel:[0,1] op_sel_hi:[1,1]
	v_add_f32_dpp v70, v70, v70 row_ror:1 row_mask:0xf bank_mask:0xf bound_ctrl:1
	v_add_f32_dpp v72, v72, v72 row_ror:1 row_mask:0xf bank_mask:0xf bound_ctrl:1
	v_pk_fma_f32 v[38:39], v[0:1], v[8:9], v[38:39]
	v_pk_fma_f32 v[82:83], v[2:3], v[10:11], v[82:83]
	v_pk_fma_f32 v[116:117], v[4:5], v[8:9], v[116:117]
	v_pk_fma_f32 v[114:115], v[6:7], v[10:11], v[114:115]
	v_pk_fma_f32 v[0:1], v[16:17], v[70:71], v[38:39] op_sel_hi:[1,0,1]
	v_pk_fma_f32 v[2:3], v[18:19], v[70:71], v[82:83] op_sel_hi:[1,0,1]
	v_pk_fma_f32 v[4:5], v[16:17], v[72:73], v[116:117] op_sel_hi:[1,0,1]
	v_pk_fma_f32 v[6:7], v[18:19], v[72:73], v[114:115] op_sel_hi:[1,0,1]
	v_pk_mul_f32 v[110:111], v[2:3], v[26:27]
	v_pk_mul_f32 v[112:113], v[6:7], v[26:27]
	v_pk_fma_f32 v[110:111], v[0:1], v[24:25], v[110:111]
	v_pk_fma_f32 v[112:113], v[4:5], v[24:25], v[112:113]
	v_add_f32_e32 v110, v110, v111
	v_add_f32_e32 v112, v112, v113
	ds_write_b32 v119, v110 offset:0
	ds_write_b32 v119, v112 offset:64
	s_waitcnt lgkmcnt(2)
	v_pk_mul_f32 v[110:111], v[2:3], v[36:37]
	v_pk_mul_f32 v[112:113], v[6:7], v[36:37]
	v_pk_fma_f32 v[110:111], v[0:1], v[34:35], v[110:111]
	v_pk_fma_f32 v[112:113], v[4:5], v[34:35], v[112:113]
	ds_read_b128 v[12:15], v69 offset:3328
	ds_read_b128 v[20:23], v69 offset:3840
	ds_read_b64 v[28:29], v118 offset:4352
	ds_read_b128 v[8:11], v69 offset:3072
	ds_read_b128 v[16:19], v69 offset:3584
	ds_read_b128 v[24:27], v69 offset:4096
	v_add_f32_e32 v70, v110, v111
	v_add_f32_e32 v72, v112, v113
	v_pk_mul_f32 v[38:39], v[78:79], v[108:109] op_sel_hi:[1,0]
	v_add_f32_dpp v70, v70, v70 row_ror:8 row_mask:0xf bank_mask:0xf bound_ctrl:1
	v_add_f32_dpp v72, v72, v72 row_ror:8 row_mask:0xf bank_mask:0xf bound_ctrl:1
	v_pk_mul_f32 v[82:83], v[80:81], v[108:109] op_sel_hi:[1,0]
	v_add_f32_dpp v70, v70, v70 row_ror:4 row_mask:0xf bank_mask:0xf bound_ctrl:1
	v_add_f32_dpp v72, v72, v72 row_ror:4 row_mask:0xf bank_mask:0xf bound_ctrl:1
	v_pk_mul_f32 v[116:117], v[78:79], v[108:109] op_sel:[0,1] op_sel_hi:[1,1]
	v_add_f32_dpp v70, v70, v70 row_ror:2 row_mask:0xf bank_mask:0xf bound_ctrl:1
	v_add_f32_dpp v72, v72, v72 row_ror:2 row_mask:0xf bank_mask:0xf bound_ctrl:1
	v_pk_mul_f32 v[114:115], v[80:81], v[108:109] op_sel:[0,1] op_sel_hi:[1,1]
	v_add_f32_dpp v70, v70, v70 row_ror:1 row_mask:0xf bank_mask:0xf bound_ctrl:1
	v_add_f32_dpp v72, v72, v72 row_ror:1 row_mask:0xf bank_mask:0xf bound_ctrl:1
	v_pk_fma_f32 v[38:39], v[0:1], v[30:31], v[38:39]
	v_pk_fma_f32 v[82:83], v[2:3], v[32:33], v[82:83]
	v_pk_fma_f32 v[116:117], v[4:5], v[30:31], v[116:117]
	v_pk_fma_f32 v[114:115], v[6:7], v[32:33], v[114:115]
	v_pk_fma_f32 v[0:1], v[74:75], v[70:71], v[38:39] op_sel_hi:[1,0,1]
	v_pk_fma_f32 v[2:3], v[76:77], v[70:71], v[82:83] op_sel_hi:[1,0,1]
	v_pk_fma_f32 v[4:5], v[74:75], v[72:73], v[116:117] op_sel_hi:[1,0,1]
	v_pk_fma_f32 v[6:7], v[76:77], v[72:73], v[114:115] op_sel_hi:[1,0,1]
	v_pk_mul_f32 v[110:111], v[2:3], v[106:107]
	v_pk_mul_f32 v[112:113], v[6:7], v[106:107]
	v_pk_fma_f32 v[110:111], v[0:1], v[104:105], v[110:111]
	v_pk_fma_f32 v[112:113], v[4:5], v[104:105], v[112:113]
	v_add_f32_e32 v110, v110, v111
	v_add_f32_e32 v112, v112, v113
	ds_write_b32 v119, v110 offset:2048
	ds_write_b32 v119, v112 offset:2112
	s_waitcnt lgkmcnt(2)
	v_pk_mul_f32 v[110:111], v[2:3], v[14:15]
	v_pk_mul_f32 v[112:113], v[6:7], v[14:15]
	v_pk_fma_f32 v[110:111], v[0:1], v[12:13], v[110:111]
	v_pk_fma_f32 v[112:113], v[4:5], v[12:13], v[112:113]
	ds_read_b128 v[34:37], v69 offset:4864
	ds_read_b128 v[78:81], v69 offset:5376
	ds_read_b64 v[108:109], v118 offset:5888
	ds_read_b128 v[30:33], v69 offset:4608
	ds_read_b128 v[74:77], v69 offset:5120
	ds_read_b128 v[104:107], v69 offset:5632
	v_add_f32_e32 v70, v110, v111
	v_add_f32_e32 v72, v112, v113
	v_pk_mul_f32 v[38:39], v[20:21], v[28:29] op_sel_hi:[1,0]
	v_add_f32_dpp v70, v70, v70 row_ror:8 row_mask:0xf bank_mask:0xf bound_ctrl:1
	v_add_f32_dpp v72, v72, v72 row_ror:8 row_mask:0xf bank_mask:0xf bound_ctrl:1
	v_pk_mul_f32 v[82:83], v[22:23], v[28:29] op_sel_hi:[1,0]
	v_add_f32_dpp v70, v70, v70 row_ror:4 row_mask:0xf bank_mask:0xf bound_ctrl:1
	v_add_f32_dpp v72, v72, v72 row_ror:4 row_mask:0xf bank_mask:0xf bound_ctrl:1
	v_pk_mul_f32 v[116:117], v[20:21], v[28:29] op_sel:[0,1] op_sel_hi:[1,1]
	v_add_f32_dpp v70, v70, v70 row_ror:2 row_mask:0xf bank_mask:0xf bound_ctrl:1
	v_add_f32_dpp v72, v72, v72 row_ror:2 row_mask:0xf bank_mask:0xf bound_ctrl:1
	v_pk_mul_f32 v[114:115], v[22:23], v[28:29] op_sel:[0,1] op_sel_hi:[1,1]
	v_add_f32_dpp v70, v70, v70 row_ror:1 row_mask:0xf bank_mask:0xf bound_ctrl:1
	v_add_f32_dpp v72, v72, v72 row_ror:1 row_mask:0xf bank_mask:0xf bound_ctrl:1
	v_pk_fma_f32 v[38:39], v[0:1], v[8:9], v[38:39]
	v_pk_fma_f32 v[82:83], v[2:3], v[10:11], v[82:83]
	v_pk_fma_f32 v[116:117], v[4:5], v[8:9], v[116:117]
	v_pk_fma_f32 v[114:115], v[6:7], v[10:11], v[114:115]
	v_pk_fma_f32 v[0:1], v[16:17], v[70:71], v[38:39] op_sel_hi:[1,0,1]
	v_pk_fma_f32 v[2:3], v[18:19], v[70:71], v[82:83] op_sel_hi:[1,0,1]
	v_pk_fma_f32 v[4:5], v[16:17], v[72:73], v[116:117] op_sel_hi:[1,0,1]
	v_pk_fma_f32 v[6:7], v[18:19], v[72:73], v[114:115] op_sel_hi:[1,0,1]
	v_pk_mul_f32 v[110:111], v[2:3], v[26:27]
	v_pk_mul_f32 v[112:113], v[6:7], v[26:27]
	v_pk_fma_f32 v[110:111], v[0:1], v[24:25], v[110:111]
	v_pk_fma_f32 v[112:113], v[4:5], v[24:25], v[112:113]
	v_add_f32_e32 v110, v110, v111
	v_add_f32_e32 v112, v112, v113
	ds_write_b32 v119, v110 offset:4096
	ds_write_b32 v119, v112 offset:4160
	s_waitcnt lgkmcnt(2)
	v_pk_mul_f32 v[110:111], v[2:3], v[36:37]
	v_pk_mul_f32 v[112:113], v[6:7], v[36:37]
	v_pk_fma_f32 v[110:111], v[0:1], v[34:35], v[110:111]
	v_pk_fma_f32 v[112:113], v[4:5], v[34:35], v[112:113]
	ds_read_b128 v[12:15], v69 offset:6400
	ds_read_b128 v[20:23], v69 offset:6912
	ds_read_b64 v[28:29], v118 offset:7424
	ds_read_b128 v[8:11], v69 offset:6144
	ds_read_b128 v[16:19], v69 offset:6656
	ds_read_b128 v[24:27], v69 offset:7168
	v_add_f32_e32 v70, v110, v111
	v_add_f32_e32 v72, v112, v113
	v_pk_mul_f32 v[38:39], v[78:79], v[108:109] op_sel_hi:[1,0]
	v_add_f32_dpp v70, v70, v70 row_ror:8 row_mask:0xf bank_mask:0xf bound_ctrl:1
	v_add_f32_dpp v72, v72, v72 row_ror:8 row_mask:0xf bank_mask:0xf bound_ctrl:1
	v_pk_mul_f32 v[82:83], v[80:81], v[108:109] op_sel_hi:[1,0]
	v_add_f32_dpp v70, v70, v70 row_ror:4 row_mask:0xf bank_mask:0xf bound_ctrl:1
	v_add_f32_dpp v72, v72, v72 row_ror:4 row_mask:0xf bank_mask:0xf bound_ctrl:1
	v_pk_mul_f32 v[116:117], v[78:79], v[108:109] op_sel:[0,1] op_sel_hi:[1,1]
	v_add_f32_dpp v70, v70, v70 row_ror:2 row_mask:0xf bank_mask:0xf bound_ctrl:1
	v_add_f32_dpp v72, v72, v72 row_ror:2 row_mask:0xf bank_mask:0xf bound_ctrl:1
	v_pk_mul_f32 v[114:115], v[80:81], v[108:109] op_sel:[0,1] op_sel_hi:[1,1]
	v_add_f32_dpp v70, v70, v70 row_ror:1 row_mask:0xf bank_mask:0xf bound_ctrl:1
	v_add_f32_dpp v72, v72, v72 row_ror:1 row_mask:0xf bank_mask:0xf bound_ctrl:1
	v_pk_fma_f32 v[38:39], v[0:1], v[30:31], v[38:39]
	v_pk_fma_f32 v[82:83], v[2:3], v[32:33], v[82:83]
	v_pk_fma_f32 v[116:117], v[4:5], v[30:31], v[116:117]
	v_pk_fma_f32 v[114:115], v[6:7], v[32:33], v[114:115]
	v_pk_fma_f32 v[0:1], v[74:75], v[70:71], v[38:39] op_sel_hi:[1,0,1]
	v_pk_fma_f32 v[2:3], v[76:77], v[70:71], v[82:83] op_sel_hi:[1,0,1]
	v_pk_fma_f32 v[4:5], v[74:75], v[72:73], v[116:117] op_sel_hi:[1,0,1]
	v_pk_fma_f32 v[6:7], v[76:77], v[72:73], v[114:115] op_sel_hi:[1,0,1]
	v_pk_mul_f32 v[110:111], v[2:3], v[106:107]
	v_pk_mul_f32 v[112:113], v[6:7], v[106:107]
	v_pk_fma_f32 v[110:111], v[0:1], v[104:105], v[110:111]
	v_pk_fma_f32 v[112:113], v[4:5], v[104:105], v[112:113]
	v_add_f32_e32 v110, v110, v111
	v_add_f32_e32 v112, v112, v113
	ds_write_b32 v119, v110 offset:6144
	ds_write_b32 v119, v112 offset:6208
	s_waitcnt lgkmcnt(2)
	v_pk_mul_f32 v[110:111], v[2:3], v[14:15]
	v_pk_mul_f32 v[112:113], v[6:7], v[14:15]
	v_pk_fma_f32 v[110:111], v[0:1], v[12:13], v[110:111]
	v_pk_fma_f32 v[112:113], v[4:5], v[12:13], v[112:113]
	ds_read_b128 v[34:37], v69 offset:7936
	ds_read_b128 v[78:81], v69 offset:8448
	ds_read_b64 v[108:109], v118 offset:8960
	ds_read_b128 v[30:33], v69 offset:7680
	ds_read_b128 v[74:77], v69 offset:8192
	ds_read_b128 v[104:107], v69 offset:8704
	v_add_f32_e32 v70, v110, v111
	v_add_f32_e32 v72, v112, v113
	v_pk_mul_f32 v[38:39], v[20:21], v[28:29] op_sel_hi:[1,0]
	v_add_f32_dpp v70, v70, v70 row_ror:8 row_mask:0xf bank_mask:0xf bound_ctrl:1
	v_add_f32_dpp v72, v72, v72 row_ror:8 row_mask:0xf bank_mask:0xf bound_ctrl:1
	v_pk_mul_f32 v[82:83], v[22:23], v[28:29] op_sel_hi:[1,0]
	v_add_f32_dpp v70, v70, v70 row_ror:4 row_mask:0xf bank_mask:0xf bound_ctrl:1
	v_add_f32_dpp v72, v72, v72 row_ror:4 row_mask:0xf bank_mask:0xf bound_ctrl:1
	v_pk_mul_f32 v[116:117], v[20:21], v[28:29] op_sel:[0,1] op_sel_hi:[1,1]
	v_add_f32_dpp v70, v70, v70 row_ror:2 row_mask:0xf bank_mask:0xf bound_ctrl:1
	v_add_f32_dpp v72, v72, v72 row_ror:2 row_mask:0xf bank_mask:0xf bound_ctrl:1
	v_pk_mul_f32 v[114:115], v[22:23], v[28:29] op_sel:[0,1] op_sel_hi:[1,1]
	v_add_f32_dpp v70, v70, v70 row_ror:1 row_mask:0xf bank_mask:0xf bound_ctrl:1
	v_add_f32_dpp v72, v72, v72 row_ror:1 row_mask:0xf bank_mask:0xf bound_ctrl:1
	v_pk_fma_f32 v[38:39], v[0:1], v[8:9], v[38:39]
	v_pk_fma_f32 v[82:83], v[2:3], v[10:11], v[82:83]
	v_pk_fma_f32 v[116:117], v[4:5], v[8:9], v[116:117]
	v_pk_fma_f32 v[114:115], v[6:7], v[10:11], v[114:115]
	v_pk_fma_f32 v[0:1], v[16:17], v[70:71], v[38:39] op_sel_hi:[1,0,1]
	v_pk_fma_f32 v[2:3], v[18:19], v[70:71], v[82:83] op_sel_hi:[1,0,1]
	v_pk_fma_f32 v[4:5], v[16:17], v[72:73], v[116:117] op_sel_hi:[1,0,1]
	v_pk_fma_f32 v[6:7], v[18:19], v[72:73], v[114:115] op_sel_hi:[1,0,1]
	v_pk_mul_f32 v[110:111], v[2:3], v[26:27]
	v_pk_mul_f32 v[112:113], v[6:7], v[26:27]
	v_pk_fma_f32 v[110:111], v[0:1], v[24:25], v[110:111]
	v_pk_fma_f32 v[112:113], v[4:5], v[24:25], v[112:113]
	v_add_f32_e32 v110, v110, v111
	v_add_f32_e32 v112, v112, v113
	ds_write_b32 v119, v110 offset:8192
	ds_write_b32 v119, v112 offset:8256
	s_waitcnt lgkmcnt(2)
	v_pk_mul_f32 v[110:111], v[2:3], v[36:37]
	v_pk_mul_f32 v[112:113], v[6:7], v[36:37]
	v_pk_fma_f32 v[110:111], v[0:1], v[34:35], v[110:111]
	v_pk_fma_f32 v[112:113], v[4:5], v[34:35], v[112:113]
	ds_read_b128 v[12:15], v69 offset:9472
	ds_read_b128 v[20:23], v69 offset:9984
	ds_read_b64 v[28:29], v118 offset:10496
	ds_read_b128 v[8:11], v69 offset:9216
	ds_read_b128 v[16:19], v69 offset:9728
	ds_read_b128 v[24:27], v69 offset:10240
	v_add_f32_e32 v70, v110, v111
	v_add_f32_e32 v72, v112, v113
	v_pk_mul_f32 v[38:39], v[78:79], v[108:109] op_sel_hi:[1,0]
	v_add_f32_dpp v70, v70, v70 row_ror:8 row_mask:0xf bank_mask:0xf bound_ctrl:1
	v_add_f32_dpp v72, v72, v72 row_ror:8 row_mask:0xf bank_mask:0xf bound_ctrl:1
	v_pk_mul_f32 v[82:83], v[80:81], v[108:109] op_sel_hi:[1,0]
	v_add_f32_dpp v70, v70, v70 row_ror:4 row_mask:0xf bank_mask:0xf bound_ctrl:1
	v_add_f32_dpp v72, v72, v72 row_ror:4 row_mask:0xf bank_mask:0xf bound_ctrl:1
	v_pk_mul_f32 v[116:117], v[78:79], v[108:109] op_sel:[0,1] op_sel_hi:[1,1]
	v_add_f32_dpp v70, v70, v70 row_ror:2 row_mask:0xf bank_mask:0xf bound_ctrl:1
	v_add_f32_dpp v72, v72, v72 row_ror:2 row_mask:0xf bank_mask:0xf bound_ctrl:1
	v_pk_mul_f32 v[114:115], v[80:81], v[108:109] op_sel:[0,1] op_sel_hi:[1,1]
	v_add_f32_dpp v70, v70, v70 row_ror:1 row_mask:0xf bank_mask:0xf bound_ctrl:1
	v_add_f32_dpp v72, v72, v72 row_ror:1 row_mask:0xf bank_mask:0xf bound_ctrl:1
	v_pk_fma_f32 v[38:39], v[0:1], v[30:31], v[38:39]
	v_pk_fma_f32 v[82:83], v[2:3], v[32:33], v[82:83]
	v_pk_fma_f32 v[116:117], v[4:5], v[30:31], v[116:117]
	v_pk_fma_f32 v[114:115], v[6:7], v[32:33], v[114:115]
	v_pk_fma_f32 v[0:1], v[74:75], v[70:71], v[38:39] op_sel_hi:[1,0,1]
	v_pk_fma_f32 v[2:3], v[76:77], v[70:71], v[82:83] op_sel_hi:[1,0,1]
	v_pk_fma_f32 v[4:5], v[74:75], v[72:73], v[116:117] op_sel_hi:[1,0,1]
	v_pk_fma_f32 v[6:7], v[76:77], v[72:73], v[114:115] op_sel_hi:[1,0,1]
	v_pk_mul_f32 v[110:111], v[2:3], v[106:107]
	v_pk_mul_f32 v[112:113], v[6:7], v[106:107]
	v_pk_fma_f32 v[110:111], v[0:1], v[104:105], v[110:111]
	v_pk_fma_f32 v[112:113], v[4:5], v[104:105], v[112:113]
	v_add_f32_e32 v110, v110, v111
	v_add_f32_e32 v112, v112, v113
	ds_write_b32 v119, v110 offset:10240
	ds_write_b32 v119, v112 offset:10304
	s_waitcnt lgkmcnt(2)
	v_pk_mul_f32 v[110:111], v[2:3], v[14:15]
	v_pk_mul_f32 v[112:113], v[6:7], v[14:15]
	v_pk_fma_f32 v[110:111], v[0:1], v[12:13], v[110:111]
	v_pk_fma_f32 v[112:113], v[4:5], v[12:13], v[112:113]
	ds_read_b128 v[34:37], v69 offset:11008
	ds_read_b128 v[78:81], v69 offset:11520
	ds_read_b64 v[108:109], v118 offset:12032
	ds_read_b128 v[30:33], v69 offset:10752
	ds_read_b128 v[74:77], v69 offset:11264
	ds_read_b128 v[104:107], v69 offset:11776
	v_add_f32_e32 v70, v110, v111
	v_add_f32_e32 v72, v112, v113
	v_pk_mul_f32 v[38:39], v[20:21], v[28:29] op_sel_hi:[1,0]
	v_add_f32_dpp v70, v70, v70 row_ror:8 row_mask:0xf bank_mask:0xf bound_ctrl:1
	v_add_f32_dpp v72, v72, v72 row_ror:8 row_mask:0xf bank_mask:0xf bound_ctrl:1
	v_pk_mul_f32 v[82:83], v[22:23], v[28:29] op_sel_hi:[1,0]
	v_add_f32_dpp v70, v70, v70 row_ror:4 row_mask:0xf bank_mask:0xf bound_ctrl:1
	v_add_f32_dpp v72, v72, v72 row_ror:4 row_mask:0xf bank_mask:0xf bound_ctrl:1
	v_pk_mul_f32 v[116:117], v[20:21], v[28:29] op_sel:[0,1] op_sel_hi:[1,1]
	v_add_f32_dpp v70, v70, v70 row_ror:2 row_mask:0xf bank_mask:0xf bound_ctrl:1
	v_add_f32_dpp v72, v72, v72 row_ror:2 row_mask:0xf bank_mask:0xf bound_ctrl:1
	v_pk_mul_f32 v[114:115], v[22:23], v[28:29] op_sel:[0,1] op_sel_hi:[1,1]
	v_add_f32_dpp v70, v70, v70 row_ror:1 row_mask:0xf bank_mask:0xf bound_ctrl:1
	v_add_f32_dpp v72, v72, v72 row_ror:1 row_mask:0xf bank_mask:0xf bound_ctrl:1
	v_pk_fma_f32 v[38:39], v[0:1], v[8:9], v[38:39]
	v_pk_fma_f32 v[82:83], v[2:3], v[10:11], v[82:83]
	v_pk_fma_f32 v[116:117], v[4:5], v[8:9], v[116:117]
	v_pk_fma_f32 v[114:115], v[6:7], v[10:11], v[114:115]
	v_pk_fma_f32 v[0:1], v[16:17], v[70:71], v[38:39] op_sel_hi:[1,0,1]
	v_pk_fma_f32 v[2:3], v[18:19], v[70:71], v[82:83] op_sel_hi:[1,0,1]
	v_pk_fma_f32 v[4:5], v[16:17], v[72:73], v[116:117] op_sel_hi:[1,0,1]
	v_pk_fma_f32 v[6:7], v[18:19], v[72:73], v[114:115] op_sel_hi:[1,0,1]
	v_pk_mul_f32 v[110:111], v[2:3], v[26:27]
	v_pk_mul_f32 v[112:113], v[6:7], v[26:27]
	v_pk_fma_f32 v[110:111], v[0:1], v[24:25], v[110:111]
	v_pk_fma_f32 v[112:113], v[4:5], v[24:25], v[112:113]
	v_add_f32_e32 v110, v110, v111
	v_add_f32_e32 v112, v112, v113
	ds_write_b32 v119, v110 offset:12288
	ds_write_b32 v119, v112 offset:12352
	s_waitcnt lgkmcnt(2)
	v_pk_mul_f32 v[110:111], v[2:3], v[36:37]
	v_pk_mul_f32 v[112:113], v[6:7], v[36:37]
	v_pk_fma_f32 v[110:111], v[0:1], v[34:35], v[110:111]
	v_pk_fma_f32 v[112:113], v[4:5], v[34:35], v[112:113]
	ds_read_b128 v[12:15], v69 offset:12544
	ds_read_b128 v[20:23], v69 offset:13056
	ds_read_b64 v[28:29], v118 offset:13568
	ds_read_b128 v[8:11], v69 offset:12288
	ds_read_b128 v[16:19], v69 offset:12800
	ds_read_b128 v[24:27], v69 offset:13312
	v_add_f32_e32 v70, v110, v111
	v_add_f32_e32 v72, v112, v113
	v_pk_mul_f32 v[38:39], v[78:79], v[108:109] op_sel_hi:[1,0]
	v_add_f32_dpp v70, v70, v70 row_ror:8 row_mask:0xf bank_mask:0xf bound_ctrl:1
	v_add_f32_dpp v72, v72, v72 row_ror:8 row_mask:0xf bank_mask:0xf bound_ctrl:1
	v_pk_mul_f32 v[82:83], v[80:81], v[108:109] op_sel_hi:[1,0]
	v_add_f32_dpp v70, v70, v70 row_ror:4 row_mask:0xf bank_mask:0xf bound_ctrl:1
	v_add_f32_dpp v72, v72, v72 row_ror:4 row_mask:0xf bank_mask:0xf bound_ctrl:1
	v_pk_mul_f32 v[116:117], v[78:79], v[108:109] op_sel:[0,1] op_sel_hi:[1,1]
	v_add_f32_dpp v70, v70, v70 row_ror:2 row_mask:0xf bank_mask:0xf bound_ctrl:1
	v_add_f32_dpp v72, v72, v72 row_ror:2 row_mask:0xf bank_mask:0xf bound_ctrl:1
	v_pk_mul_f32 v[114:115], v[80:81], v[108:109] op_sel:[0,1] op_sel_hi:[1,1]
	v_add_f32_dpp v70, v70, v70 row_ror:1 row_mask:0xf bank_mask:0xf bound_ctrl:1
	v_add_f32_dpp v72, v72, v72 row_ror:1 row_mask:0xf bank_mask:0xf bound_ctrl:1
	v_pk_fma_f32 v[38:39], v[0:1], v[30:31], v[38:39]
	v_pk_fma_f32 v[82:83], v[2:3], v[32:33], v[82:83]
	v_pk_fma_f32 v[116:117], v[4:5], v[30:31], v[116:117]
	v_pk_fma_f32 v[114:115], v[6:7], v[32:33], v[114:115]
	v_pk_fma_f32 v[0:1], v[74:75], v[70:71], v[38:39] op_sel_hi:[1,0,1]
	v_pk_fma_f32 v[2:3], v[76:77], v[70:71], v[82:83] op_sel_hi:[1,0,1]
	v_pk_fma_f32 v[4:5], v[74:75], v[72:73], v[116:117] op_sel_hi:[1,0,1]
	v_pk_fma_f32 v[6:7], v[76:77], v[72:73], v[114:115] op_sel_hi:[1,0,1]
	v_pk_mul_f32 v[110:111], v[2:3], v[106:107]
	v_pk_mul_f32 v[112:113], v[6:7], v[106:107]
	v_pk_fma_f32 v[110:111], v[0:1], v[104:105], v[110:111]
	v_pk_fma_f32 v[112:113], v[4:5], v[104:105], v[112:113]
	v_add_f32_e32 v110, v110, v111
	v_add_f32_e32 v112, v112, v113
	ds_write_b32 v119, v110 offset:14336
	ds_write_b32 v119, v112 offset:14400
	s_waitcnt lgkmcnt(2)
	v_pk_mul_f32 v[110:111], v[2:3], v[14:15]
	v_pk_mul_f32 v[112:113], v[6:7], v[14:15]
	v_pk_fma_f32 v[110:111], v[0:1], v[12:13], v[110:111]
	v_pk_fma_f32 v[112:113], v[4:5], v[12:13], v[112:113]
	ds_read_b128 v[34:37], v69 offset:14080
	ds_read_b128 v[78:81], v69 offset:14592
	ds_read_b64 v[108:109], v118 offset:15104
	ds_read_b128 v[30:33], v69 offset:13824
	ds_read_b128 v[74:77], v69 offset:14336
	ds_read_b128 v[104:107], v69 offset:14848
	v_add_f32_e32 v70, v110, v111
	v_add_f32_e32 v72, v112, v113
	v_pk_mul_f32 v[38:39], v[20:21], v[28:29] op_sel_hi:[1,0]
	v_add_f32_dpp v70, v70, v70 row_ror:8 row_mask:0xf bank_mask:0xf bound_ctrl:1
	v_add_f32_dpp v72, v72, v72 row_ror:8 row_mask:0xf bank_mask:0xf bound_ctrl:1
	v_pk_mul_f32 v[82:83], v[22:23], v[28:29] op_sel_hi:[1,0]
	v_add_f32_dpp v70, v70, v70 row_ror:4 row_mask:0xf bank_mask:0xf bound_ctrl:1
	v_add_f32_dpp v72, v72, v72 row_ror:4 row_mask:0xf bank_mask:0xf bound_ctrl:1
	v_pk_mul_f32 v[116:117], v[20:21], v[28:29] op_sel:[0,1] op_sel_hi:[1,1]
	v_add_f32_dpp v70, v70, v70 row_ror:2 row_mask:0xf bank_mask:0xf bound_ctrl:1
	v_add_f32_dpp v72, v72, v72 row_ror:2 row_mask:0xf bank_mask:0xf bound_ctrl:1
	v_pk_mul_f32 v[114:115], v[22:23], v[28:29] op_sel:[0,1] op_sel_hi:[1,1]
	v_add_f32_dpp v70, v70, v70 row_ror:1 row_mask:0xf bank_mask:0xf bound_ctrl:1
	v_add_f32_dpp v72, v72, v72 row_ror:1 row_mask:0xf bank_mask:0xf bound_ctrl:1
	v_pk_fma_f32 v[38:39], v[0:1], v[8:9], v[38:39]
	v_pk_fma_f32 v[82:83], v[2:3], v[10:11], v[82:83]
	v_pk_fma_f32 v[116:117], v[4:5], v[8:9], v[116:117]
	v_pk_fma_f32 v[114:115], v[6:7], v[10:11], v[114:115]
	v_pk_fma_f32 v[0:1], v[16:17], v[70:71], v[38:39] op_sel_hi:[1,0,1]
	v_pk_fma_f32 v[2:3], v[18:19], v[70:71], v[82:83] op_sel_hi:[1,0,1]
	v_pk_fma_f32 v[4:5], v[16:17], v[72:73], v[116:117] op_sel_hi:[1,0,1]
	v_pk_fma_f32 v[6:7], v[18:19], v[72:73], v[114:115] op_sel_hi:[1,0,1]
	v_pk_mul_f32 v[110:111], v[2:3], v[26:27]
	v_pk_mul_f32 v[112:113], v[6:7], v[26:27]
	v_pk_fma_f32 v[110:111], v[0:1], v[24:25], v[110:111]
	v_pk_fma_f32 v[112:113], v[4:5], v[24:25], v[112:113]
	v_add_f32_e32 v110, v110, v111
	v_add_f32_e32 v112, v112, v113
	ds_write_b32 v119, v110 offset:16384
	ds_write_b32 v119, v112 offset:16448
	s_waitcnt lgkmcnt(2)
	v_pk_mul_f32 v[110:111], v[2:3], v[36:37]
	v_pk_mul_f32 v[112:113], v[6:7], v[36:37]
	v_pk_fma_f32 v[110:111], v[0:1], v[34:35], v[110:111]
	v_pk_fma_f32 v[112:113], v[4:5], v[34:35], v[112:113]
	ds_read_b128 v[12:15], v69 offset:15616
	ds_read_b128 v[20:23], v69 offset:16128
	ds_read_b64 v[28:29], v118 offset:16640
	ds_read_b128 v[8:11], v69 offset:15360
	ds_read_b128 v[16:19], v69 offset:15872
	ds_read_b128 v[24:27], v69 offset:16384
	v_add_f32_e32 v70, v110, v111
	v_add_f32_e32 v72, v112, v113
	v_pk_mul_f32 v[38:39], v[78:79], v[108:109] op_sel_hi:[1,0]
	v_add_f32_dpp v70, v70, v70 row_ror:8 row_mask:0xf bank_mask:0xf bound_ctrl:1
	v_add_f32_dpp v72, v72, v72 row_ror:8 row_mask:0xf bank_mask:0xf bound_ctrl:1
	v_pk_mul_f32 v[82:83], v[80:81], v[108:109] op_sel_hi:[1,0]
	v_add_f32_dpp v70, v70, v70 row_ror:4 row_mask:0xf bank_mask:0xf bound_ctrl:1
	v_add_f32_dpp v72, v72, v72 row_ror:4 row_mask:0xf bank_mask:0xf bound_ctrl:1
	v_pk_mul_f32 v[116:117], v[78:79], v[108:109] op_sel:[0,1] op_sel_hi:[1,1]
	v_add_f32_dpp v70, v70, v70 row_ror:2 row_mask:0xf bank_mask:0xf bound_ctrl:1
	v_add_f32_dpp v72, v72, v72 row_ror:2 row_mask:0xf bank_mask:0xf bound_ctrl:1
	v_pk_mul_f32 v[114:115], v[80:81], v[108:109] op_sel:[0,1] op_sel_hi:[1,1]
	v_add_f32_dpp v70, v70, v70 row_ror:1 row_mask:0xf bank_mask:0xf bound_ctrl:1
	v_add_f32_dpp v72, v72, v72 row_ror:1 row_mask:0xf bank_mask:0xf bound_ctrl:1
	v_pk_fma_f32 v[38:39], v[0:1], v[30:31], v[38:39]
	v_pk_fma_f32 v[82:83], v[2:3], v[32:33], v[82:83]
	v_pk_fma_f32 v[116:117], v[4:5], v[30:31], v[116:117]
	v_pk_fma_f32 v[114:115], v[6:7], v[32:33], v[114:115]
	v_pk_fma_f32 v[0:1], v[74:75], v[70:71], v[38:39] op_sel_hi:[1,0,1]
	v_pk_fma_f32 v[2:3], v[76:77], v[70:71], v[82:83] op_sel_hi:[1,0,1]
	v_pk_fma_f32 v[4:5], v[74:75], v[72:73], v[116:117] op_sel_hi:[1,0,1]
	v_pk_fma_f32 v[6:7], v[76:77], v[72:73], v[114:115] op_sel_hi:[1,0,1]
	v_pk_mul_f32 v[110:111], v[2:3], v[106:107]
	v_pk_mul_f32 v[112:113], v[6:7], v[106:107]
	v_pk_fma_f32 v[110:111], v[0:1], v[104:105], v[110:111]
	v_pk_fma_f32 v[112:113], v[4:5], v[104:105], v[112:113]
	v_add_f32_e32 v110, v110, v111
	v_add_f32_e32 v112, v112, v113
	ds_write_b32 v119, v110 offset:18432
	ds_write_b32 v119, v112 offset:18496
	s_waitcnt lgkmcnt(2)
	v_pk_mul_f32 v[110:111], v[2:3], v[14:15]
	v_pk_mul_f32 v[112:113], v[6:7], v[14:15]
	v_pk_fma_f32 v[110:111], v[0:1], v[12:13], v[110:111]
	v_pk_fma_f32 v[112:113], v[4:5], v[12:13], v[112:113]
	ds_read_b128 v[34:37], v69 offset:17152
	ds_read_b128 v[78:81], v69 offset:17664
	ds_read_b64 v[108:109], v118 offset:18176
	ds_read_b128 v[30:33], v69 offset:16896
	ds_read_b128 v[74:77], v69 offset:17408
	ds_read_b128 v[104:107], v69 offset:17920
	v_add_f32_e32 v70, v110, v111
	v_add_f32_e32 v72, v112, v113
	v_pk_mul_f32 v[38:39], v[20:21], v[28:29] op_sel_hi:[1,0]
	v_add_f32_dpp v70, v70, v70 row_ror:8 row_mask:0xf bank_mask:0xf bound_ctrl:1
	v_add_f32_dpp v72, v72, v72 row_ror:8 row_mask:0xf bank_mask:0xf bound_ctrl:1
	v_pk_mul_f32 v[82:83], v[22:23], v[28:29] op_sel_hi:[1,0]
	v_add_f32_dpp v70, v70, v70 row_ror:4 row_mask:0xf bank_mask:0xf bound_ctrl:1
	v_add_f32_dpp v72, v72, v72 row_ror:4 row_mask:0xf bank_mask:0xf bound_ctrl:1
	v_pk_mul_f32 v[116:117], v[20:21], v[28:29] op_sel:[0,1] op_sel_hi:[1,1]
	v_add_f32_dpp v70, v70, v70 row_ror:2 row_mask:0xf bank_mask:0xf bound_ctrl:1
	v_add_f32_dpp v72, v72, v72 row_ror:2 row_mask:0xf bank_mask:0xf bound_ctrl:1
	v_pk_mul_f32 v[114:115], v[22:23], v[28:29] op_sel:[0,1] op_sel_hi:[1,1]
	v_add_f32_dpp v70, v70, v70 row_ror:1 row_mask:0xf bank_mask:0xf bound_ctrl:1
	v_add_f32_dpp v72, v72, v72 row_ror:1 row_mask:0xf bank_mask:0xf bound_ctrl:1
	v_pk_fma_f32 v[38:39], v[0:1], v[8:9], v[38:39]
	v_pk_fma_f32 v[82:83], v[2:3], v[10:11], v[82:83]
	v_pk_fma_f32 v[116:117], v[4:5], v[8:9], v[116:117]
	v_pk_fma_f32 v[114:115], v[6:7], v[10:11], v[114:115]
	v_pk_fma_f32 v[0:1], v[16:17], v[70:71], v[38:39] op_sel_hi:[1,0,1]
	v_pk_fma_f32 v[2:3], v[18:19], v[70:71], v[82:83] op_sel_hi:[1,0,1]
	v_pk_fma_f32 v[4:5], v[16:17], v[72:73], v[116:117] op_sel_hi:[1,0,1]
	v_pk_fma_f32 v[6:7], v[18:19], v[72:73], v[114:115] op_sel_hi:[1,0,1]
	v_pk_mul_f32 v[110:111], v[2:3], v[26:27]
	v_pk_mul_f32 v[112:113], v[6:7], v[26:27]
	v_pk_fma_f32 v[110:111], v[0:1], v[24:25], v[110:111]
	v_pk_fma_f32 v[112:113], v[4:5], v[24:25], v[112:113]
	v_add_f32_e32 v110, v110, v111
	v_add_f32_e32 v112, v112, v113
	ds_write_b32 v119, v110 offset:20480
	ds_write_b32 v119, v112 offset:20544
	s_waitcnt lgkmcnt(2)
	v_pk_mul_f32 v[110:111], v[2:3], v[36:37]
	v_pk_mul_f32 v[112:113], v[6:7], v[36:37]
	v_pk_fma_f32 v[110:111], v[0:1], v[34:35], v[110:111]
	v_pk_fma_f32 v[112:113], v[4:5], v[34:35], v[112:113]
	ds_read_b128 v[12:15], v69 offset:18688
	ds_read_b128 v[20:23], v69 offset:19200
	ds_read_b64 v[28:29], v118 offset:19712
	ds_read_b128 v[8:11], v69 offset:18432
	ds_read_b128 v[16:19], v69 offset:18944
	ds_read_b128 v[24:27], v69 offset:19456
	v_add_f32_e32 v70, v110, v111
	v_add_f32_e32 v72, v112, v113
	v_pk_mul_f32 v[38:39], v[78:79], v[108:109] op_sel_hi:[1,0]
	v_add_f32_dpp v70, v70, v70 row_ror:8 row_mask:0xf bank_mask:0xf bound_ctrl:1
	v_add_f32_dpp v72, v72, v72 row_ror:8 row_mask:0xf bank_mask:0xf bound_ctrl:1
	v_pk_mul_f32 v[82:83], v[80:81], v[108:109] op_sel_hi:[1,0]
	v_add_f32_dpp v70, v70, v70 row_ror:4 row_mask:0xf bank_mask:0xf bound_ctrl:1
	v_add_f32_dpp v72, v72, v72 row_ror:4 row_mask:0xf bank_mask:0xf bound_ctrl:1
	v_pk_mul_f32 v[116:117], v[78:79], v[108:109] op_sel:[0,1] op_sel_hi:[1,1]
	v_add_f32_dpp v70, v70, v70 row_ror:2 row_mask:0xf bank_mask:0xf bound_ctrl:1
	v_add_f32_dpp v72, v72, v72 row_ror:2 row_mask:0xf bank_mask:0xf bound_ctrl:1
	v_pk_mul_f32 v[114:115], v[80:81], v[108:109] op_sel:[0,1] op_sel_hi:[1,1]
	v_add_f32_dpp v70, v70, v70 row_ror:1 row_mask:0xf bank_mask:0xf bound_ctrl:1
	v_add_f32_dpp v72, v72, v72 row_ror:1 row_mask:0xf bank_mask:0xf bound_ctrl:1
	v_pk_fma_f32 v[38:39], v[0:1], v[30:31], v[38:39]
	v_pk_fma_f32 v[82:83], v[2:3], v[32:33], v[82:83]
	v_pk_fma_f32 v[116:117], v[4:5], v[30:31], v[116:117]
	v_pk_fma_f32 v[114:115], v[6:7], v[32:33], v[114:115]
	v_pk_fma_f32 v[0:1], v[74:75], v[70:71], v[38:39] op_sel_hi:[1,0,1]
	v_pk_fma_f32 v[2:3], v[76:77], v[70:71], v[82:83] op_sel_hi:[1,0,1]
	v_pk_fma_f32 v[4:5], v[74:75], v[72:73], v[116:117] op_sel_hi:[1,0,1]
	v_pk_fma_f32 v[6:7], v[76:77], v[72:73], v[114:115] op_sel_hi:[1,0,1]
	v_pk_mul_f32 v[110:111], v[2:3], v[106:107]
	v_pk_mul_f32 v[112:113], v[6:7], v[106:107]
	v_pk_fma_f32 v[110:111], v[0:1], v[104:105], v[110:111]
	v_pk_fma_f32 v[112:113], v[4:5], v[104:105], v[112:113]
	v_add_f32_e32 v110, v110, v111
	v_add_f32_e32 v112, v112, v113
	ds_write_b32 v119, v110 offset:22528
	ds_write_b32 v119, v112 offset:22592
	s_waitcnt lgkmcnt(2)
	v_pk_mul_f32 v[110:111], v[2:3], v[14:15]
	v_pk_mul_f32 v[112:113], v[6:7], v[14:15]
	v_pk_fma_f32 v[110:111], v[0:1], v[12:13], v[110:111]
	v_pk_fma_f32 v[112:113], v[4:5], v[12:13], v[112:113]
	ds_read_b128 v[34:37], v69 offset:20224
	ds_read_b128 v[78:81], v69 offset:20736
	ds_read_b64 v[108:109], v118 offset:21248
	ds_read_b128 v[30:33], v69 offset:19968
	ds_read_b128 v[74:77], v69 offset:20480
	ds_read_b128 v[104:107], v69 offset:20992
	v_add_f32_e32 v70, v110, v111
	v_add_f32_e32 v72, v112, v113
	v_pk_mul_f32 v[38:39], v[20:21], v[28:29] op_sel_hi:[1,0]
	v_add_f32_dpp v70, v70, v70 row_ror:8 row_mask:0xf bank_mask:0xf bound_ctrl:1
	v_add_f32_dpp v72, v72, v72 row_ror:8 row_mask:0xf bank_mask:0xf bound_ctrl:1
	v_pk_mul_f32 v[82:83], v[22:23], v[28:29] op_sel_hi:[1,0]
	v_add_f32_dpp v70, v70, v70 row_ror:4 row_mask:0xf bank_mask:0xf bound_ctrl:1
	v_add_f32_dpp v72, v72, v72 row_ror:4 row_mask:0xf bank_mask:0xf bound_ctrl:1
	v_pk_mul_f32 v[116:117], v[20:21], v[28:29] op_sel:[0,1] op_sel_hi:[1,1]
	v_add_f32_dpp v70, v70, v70 row_ror:2 row_mask:0xf bank_mask:0xf bound_ctrl:1
	v_add_f32_dpp v72, v72, v72 row_ror:2 row_mask:0xf bank_mask:0xf bound_ctrl:1
	v_pk_mul_f32 v[114:115], v[22:23], v[28:29] op_sel:[0,1] op_sel_hi:[1,1]
	v_add_f32_dpp v70, v70, v70 row_ror:1 row_mask:0xf bank_mask:0xf bound_ctrl:1
	v_add_f32_dpp v72, v72, v72 row_ror:1 row_mask:0xf bank_mask:0xf bound_ctrl:1
	v_pk_fma_f32 v[38:39], v[0:1], v[8:9], v[38:39]
	v_pk_fma_f32 v[82:83], v[2:3], v[10:11], v[82:83]
	v_pk_fma_f32 v[116:117], v[4:5], v[8:9], v[116:117]
	v_pk_fma_f32 v[114:115], v[6:7], v[10:11], v[114:115]
	v_pk_fma_f32 v[0:1], v[16:17], v[70:71], v[38:39] op_sel_hi:[1,0,1]
	v_pk_fma_f32 v[2:3], v[18:19], v[70:71], v[82:83] op_sel_hi:[1,0,1]
	v_pk_fma_f32 v[4:5], v[16:17], v[72:73], v[116:117] op_sel_hi:[1,0,1]
	v_pk_fma_f32 v[6:7], v[18:19], v[72:73], v[114:115] op_sel_hi:[1,0,1]
	v_pk_mul_f32 v[110:111], v[2:3], v[26:27]
	v_pk_mul_f32 v[112:113], v[6:7], v[26:27]
	v_pk_fma_f32 v[110:111], v[0:1], v[24:25], v[110:111]
	v_pk_fma_f32 v[112:113], v[4:5], v[24:25], v[112:113]
	v_add_f32_e32 v110, v110, v111
	v_add_f32_e32 v112, v112, v113
	ds_write_b32 v119, v110 offset:24576
	ds_write_b32 v119, v112 offset:24640
	s_waitcnt lgkmcnt(2)
	v_pk_mul_f32 v[110:111], v[2:3], v[36:37]
	v_pk_mul_f32 v[112:113], v[6:7], v[36:37]
	v_pk_fma_f32 v[110:111], v[0:1], v[34:35], v[110:111]
	v_pk_fma_f32 v[112:113], v[4:5], v[34:35], v[112:113]
	ds_read_b128 v[12:15], v69 offset:21760
	ds_read_b128 v[20:23], v69 offset:22272
	ds_read_b64 v[28:29], v118 offset:22784
	ds_read_b128 v[8:11], v69 offset:21504
	ds_read_b128 v[16:19], v69 offset:22016
	ds_read_b128 v[24:27], v69 offset:22528
	v_add_f32_e32 v70, v110, v111
	v_add_f32_e32 v72, v112, v113
	v_pk_mul_f32 v[38:39], v[78:79], v[108:109] op_sel_hi:[1,0]
	v_add_f32_dpp v70, v70, v70 row_ror:8 row_mask:0xf bank_mask:0xf bound_ctrl:1
	v_add_f32_dpp v72, v72, v72 row_ror:8 row_mask:0xf bank_mask:0xf bound_ctrl:1
	v_pk_mul_f32 v[82:83], v[80:81], v[108:109] op_sel_hi:[1,0]
	v_add_f32_dpp v70, v70, v70 row_ror:4 row_mask:0xf bank_mask:0xf bound_ctrl:1
	v_add_f32_dpp v72, v72, v72 row_ror:4 row_mask:0xf bank_mask:0xf bound_ctrl:1
	v_pk_mul_f32 v[116:117], v[78:79], v[108:109] op_sel:[0,1] op_sel_hi:[1,1]
	v_add_f32_dpp v70, v70, v70 row_ror:2 row_mask:0xf bank_mask:0xf bound_ctrl:1
	v_add_f32_dpp v72, v72, v72 row_ror:2 row_mask:0xf bank_mask:0xf bound_ctrl:1
	v_pk_mul_f32 v[114:115], v[80:81], v[108:109] op_sel:[0,1] op_sel_hi:[1,1]
	v_add_f32_dpp v70, v70, v70 row_ror:1 row_mask:0xf bank_mask:0xf bound_ctrl:1
	v_add_f32_dpp v72, v72, v72 row_ror:1 row_mask:0xf bank_mask:0xf bound_ctrl:1
	v_pk_fma_f32 v[38:39], v[0:1], v[30:31], v[38:39]
	v_pk_fma_f32 v[82:83], v[2:3], v[32:33], v[82:83]
	v_pk_fma_f32 v[116:117], v[4:5], v[30:31], v[116:117]
	v_pk_fma_f32 v[114:115], v[6:7], v[32:33], v[114:115]
	v_pk_fma_f32 v[0:1], v[74:75], v[70:71], v[38:39] op_sel_hi:[1,0,1]
	v_pk_fma_f32 v[2:3], v[76:77], v[70:71], v[82:83] op_sel_hi:[1,0,1]
	v_pk_fma_f32 v[4:5], v[74:75], v[72:73], v[116:117] op_sel_hi:[1,0,1]
	v_pk_fma_f32 v[6:7], v[76:77], v[72:73], v[114:115] op_sel_hi:[1,0,1]
	v_pk_mul_f32 v[110:111], v[2:3], v[106:107]
	v_pk_mul_f32 v[112:113], v[6:7], v[106:107]
	v_pk_fma_f32 v[110:111], v[0:1], v[104:105], v[110:111]
	v_pk_fma_f32 v[112:113], v[4:5], v[104:105], v[112:113]
	v_add_f32_e32 v110, v110, v111
	v_add_f32_e32 v112, v112, v113
	ds_write_b32 v119, v110 offset:26624
	ds_write_b32 v119, v112 offset:26688
	s_waitcnt lgkmcnt(2)
	v_pk_mul_f32 v[110:111], v[2:3], v[14:15]
	v_pk_mul_f32 v[112:113], v[6:7], v[14:15]
	v_pk_fma_f32 v[110:111], v[0:1], v[12:13], v[110:111]
	v_pk_fma_f32 v[112:113], v[4:5], v[12:13], v[112:113]
	ds_read_b128 v[34:37], v69 offset:23296
	ds_read_b128 v[78:81], v69 offset:23808
	ds_read_b64 v[108:109], v118 offset:24320
	ds_read_b128 v[30:33], v69 offset:23040
	ds_read_b128 v[74:77], v69 offset:23552
	ds_read_b128 v[104:107], v69 offset:24064
	v_add_f32_e32 v70, v110, v111
	v_add_f32_e32 v72, v112, v113
	v_pk_mul_f32 v[38:39], v[20:21], v[28:29] op_sel_hi:[1,0]
	v_add_f32_dpp v70, v70, v70 row_ror:8 row_mask:0xf bank_mask:0xf bound_ctrl:1
	v_add_f32_dpp v72, v72, v72 row_ror:8 row_mask:0xf bank_mask:0xf bound_ctrl:1
	v_pk_mul_f32 v[82:83], v[22:23], v[28:29] op_sel_hi:[1,0]
	v_add_f32_dpp v70, v70, v70 row_ror:4 row_mask:0xf bank_mask:0xf bound_ctrl:1
	v_add_f32_dpp v72, v72, v72 row_ror:4 row_mask:0xf bank_mask:0xf bound_ctrl:1
	v_pk_mul_f32 v[116:117], v[20:21], v[28:29] op_sel:[0,1] op_sel_hi:[1,1]
	v_add_f32_dpp v70, v70, v70 row_ror:2 row_mask:0xf bank_mask:0xf bound_ctrl:1
	v_add_f32_dpp v72, v72, v72 row_ror:2 row_mask:0xf bank_mask:0xf bound_ctrl:1
	v_pk_mul_f32 v[114:115], v[22:23], v[28:29] op_sel:[0,1] op_sel_hi:[1,1]
	v_add_f32_dpp v70, v70, v70 row_ror:1 row_mask:0xf bank_mask:0xf bound_ctrl:1
	v_add_f32_dpp v72, v72, v72 row_ror:1 row_mask:0xf bank_mask:0xf bound_ctrl:1
	v_pk_fma_f32 v[38:39], v[0:1], v[8:9], v[38:39]
	v_pk_fma_f32 v[82:83], v[2:3], v[10:11], v[82:83]
	v_pk_fma_f32 v[116:117], v[4:5], v[8:9], v[116:117]
	v_pk_fma_f32 v[114:115], v[6:7], v[10:11], v[114:115]
	v_pk_fma_f32 v[0:1], v[16:17], v[70:71], v[38:39] op_sel_hi:[1,0,1]
	v_pk_fma_f32 v[2:3], v[18:19], v[70:71], v[82:83] op_sel_hi:[1,0,1]
	v_pk_fma_f32 v[4:5], v[16:17], v[72:73], v[116:117] op_sel_hi:[1,0,1]
	v_pk_fma_f32 v[6:7], v[18:19], v[72:73], v[114:115] op_sel_hi:[1,0,1]
	v_pk_mul_f32 v[110:111], v[2:3], v[26:27]
	v_pk_mul_f32 v[112:113], v[6:7], v[26:27]
	v_pk_fma_f32 v[110:111], v[0:1], v[24:25], v[110:111]
	v_pk_fma_f32 v[112:113], v[4:5], v[24:25], v[112:113]
	v_add_f32_e32 v110, v110, v111
	v_add_f32_e32 v112, v112, v113
	ds_write_b32 v119, v110 offset:28672
	ds_write_b32 v119, v112 offset:28736
	s_waitcnt lgkmcnt(2)
	v_pk_mul_f32 v[110:111], v[2:3], v[36:37]
	v_pk_mul_f32 v[112:113], v[6:7], v[36:37]
	v_pk_fma_f32 v[110:111], v[0:1], v[34:35], v[110:111]
	v_pk_fma_f32 v[112:113], v[4:5], v[34:35], v[112:113]
	v_add_f32_e32 v70, v110, v111
	v_add_f32_e32 v72, v112, v113
	v_pk_mul_f32 v[38:39], v[78:79], v[108:109] op_sel_hi:[1,0]
	v_add_f32_dpp v70, v70, v70 row_ror:8 row_mask:0xf bank_mask:0xf bound_ctrl:1
	v_add_f32_dpp v72, v72, v72 row_ror:8 row_mask:0xf bank_mask:0xf bound_ctrl:1
	v_pk_mul_f32 v[82:83], v[80:81], v[108:109] op_sel_hi:[1,0]
	v_add_f32_dpp v70, v70, v70 row_ror:4 row_mask:0xf bank_mask:0xf bound_ctrl:1
	v_add_f32_dpp v72, v72, v72 row_ror:4 row_mask:0xf bank_mask:0xf bound_ctrl:1
	v_pk_mul_f32 v[116:117], v[78:79], v[108:109] op_sel:[0,1] op_sel_hi:[1,1]
	v_add_f32_dpp v70, v70, v70 row_ror:2 row_mask:0xf bank_mask:0xf bound_ctrl:1
	v_add_f32_dpp v72, v72, v72 row_ror:2 row_mask:0xf bank_mask:0xf bound_ctrl:1
	v_pk_mul_f32 v[114:115], v[80:81], v[108:109] op_sel:[0,1] op_sel_hi:[1,1]
	v_add_f32_dpp v70, v70, v70 row_ror:1 row_mask:0xf bank_mask:0xf bound_ctrl:1
	v_add_f32_dpp v72, v72, v72 row_ror:1 row_mask:0xf bank_mask:0xf bound_ctrl:1
	v_pk_fma_f32 v[38:39], v[0:1], v[30:31], v[38:39]
	v_pk_fma_f32 v[82:83], v[2:3], v[32:33], v[82:83]
	v_pk_fma_f32 v[116:117], v[4:5], v[30:31], v[116:117]
	v_pk_fma_f32 v[114:115], v[6:7], v[32:33], v[114:115]
	v_pk_fma_f32 v[0:1], v[74:75], v[70:71], v[38:39] op_sel_hi:[1,0,1]
	v_pk_fma_f32 v[2:3], v[76:77], v[70:71], v[82:83] op_sel_hi:[1,0,1]
	v_pk_fma_f32 v[4:5], v[74:75], v[72:73], v[116:117] op_sel_hi:[1,0,1]
	v_pk_fma_f32 v[6:7], v[76:77], v[72:73], v[114:115] op_sel_hi:[1,0,1]
	v_pk_mul_f32 v[110:111], v[2:3], v[106:107]
	v_pk_mul_f32 v[112:113], v[6:7], v[106:107]
	v_pk_fma_f32 v[110:111], v[0:1], v[104:105], v[110:111]
	v_pk_fma_f32 v[112:113], v[4:5], v[104:105], v[112:113]
	v_add_f32_e32 v110, v110, v111
	v_add_f32_e32 v112, v112, v113
	ds_write_b32 v119, v110 offset:30720
	ds_write_b32 v119, v112 offset:30784
	s_setprio 0

.LBB0_151:
	s_andn2_saveexec_b64 s[10:11], s[12:13]
	s_cbranch_execz .LBB0_140
	v_bfe_u32 v119, v171, 4, 2
	v_lshl_add_u32 v118, v119, 2, v100
	v_lshl_add_u32 v119, v119, 6, v94
	v_add_u32_e32 v119, 0x18000, v119
	ds_read_b128 v[12:15], v69 offset:24832
	ds_read_b128 v[20:23], v69 offset:25344
	ds_read_b64 v[28:29], v118 offset:25856
	ds_read_b128 v[8:11], v69 offset:24576
	ds_read_b128 v[16:19], v69 offset:25088
	ds_read_b128 v[24:27], v69 offset:25600
	s_setprio 3
	s_waitcnt lgkmcnt(0)
	v_pk_mul_f32 v[110:111], v[2:3], v[14:15]
	v_pk_mul_f32 v[112:113], v[6:7], v[14:15]
	v_pk_fma_f32 v[110:111], v[0:1], v[12:13], v[110:111]
	v_pk_fma_f32 v[112:113], v[4:5], v[12:13], v[112:113]
	ds_read_b128 v[34:37], v69 offset:26368
	ds_read_b128 v[78:81], v69 offset:26880
	ds_read_b64 v[108:109], v118 offset:27392
	ds_read_b128 v[30:33], v69 offset:26112
	ds_read_b128 v[74:77], v69 offset:26624
	ds_read_b128 v[104:107], v69 offset:27136
	v_add_f32_e32 v70, v110, v111
	v_add_f32_e32 v72, v112, v113
	v_pk_mul_f32 v[38:39], v[20:21], v[28:29] op_sel_hi:[1,0]
	v_add_f32_dpp v70, v70, v70 row_ror:8 row_mask:0xf bank_mask:0xf bound_ctrl:1
	v_add_f32_dpp v72, v72, v72 row_ror:8 row_mask:0xf bank_mask:0xf bound_ctrl:1
	v_pk_mul_f32 v[82:83], v[22:23], v[28:29] op_sel_hi:[1,0]
	v_add_f32_dpp v70, v70, v70 row_ror:4 row_mask:0xf bank_mask:0xf bound_ctrl:1
	v_add_f32_dpp v72, v72, v72 row_ror:4 row_mask:0xf bank_mask:0xf bound_ctrl:1
	v_pk_mul_f32 v[116:117], v[20:21], v[28:29] op_sel:[0,1] op_sel_hi:[1,1]
	v_add_f32_dpp v70, v70, v70 row_ror:2 row_mask:0xf bank_mask:0xf bound_ctrl:1
	v_add_f32_dpp v72, v72, v72 row_ror:2 row_mask:0xf bank_mask:0xf bound_ctrl:1
	v_pk_mul_f32 v[114:115], v[22:23], v[28:29] op_sel:[0,1] op_sel_hi:[1,1]
	v_add_f32_dpp v70, v70, v70 row_ror:1 row_mask:0xf bank_mask:0xf bound_ctrl:1
	v_add_f32_dpp v72, v72, v72 row_ror:1 row_mask:0xf bank_mask:0xf bound_ctrl:1
	v_pk_fma_f32 v[38:39], v[0:1], v[8:9], v[38:39]
	v_pk_fma_f32 v[82:83], v[2:3], v[10:11], v[82:83]
	v_pk_fma_f32 v[116:117], v[4:5], v[8:9], v[116:117]
	v_pk_fma_f32 v[114:115], v[6:7], v[10:11], v[114:115]
	v_pk_fma_f32 v[0:1], v[16:17], v[70:71], v[38:39] op_sel_hi:[1,0,1]
	v_pk_fma_f32 v[2:3], v[18:19], v[70:71], v[82:83] op_sel_hi:[1,0,1]
	v_pk_fma_f32 v[4:5], v[16:17], v[72:73], v[116:117] op_sel_hi:[1,0,1]
	v_pk_fma_f32 v[6:7], v[18:19], v[72:73], v[114:115] op_sel_hi:[1,0,1]
	v_pk_mul_f32 v[110:111], v[2:3], v[26:27]
	v_pk_mul_f32 v[112:113], v[6:7], v[26:27]
	v_pk_fma_f32 v[110:111], v[0:1], v[24:25], v[110:111]
	v_pk_fma_f32 v[112:113], v[4:5], v[24:25], v[112:113]
	v_add_f32_e32 v110, v110, v111
	v_add_f32_e32 v112, v112, v113
	ds_write_b32 v119, v110 offset:0
	ds_write_b32 v119, v112 offset:64
	s_waitcnt lgkmcnt(2)
	v_pk_mul_f32 v[110:111], v[2:3], v[36:37]
	v_pk_mul_f32 v[112:113], v[6:7], v[36:37]
	v_pk_fma_f32 v[110:111], v[0:1], v[34:35], v[110:111]
	v_pk_fma_f32 v[112:113], v[4:5], v[34:35], v[112:113]
	ds_read_b128 v[12:15], v69 offset:27904
	ds_read_b128 v[20:23], v69 offset:28416
	ds_read_b64 v[28:29], v118 offset:28928
	ds_read_b128 v[8:11], v69 offset:27648
	ds_read_b128 v[16:19], v69 offset:28160
	ds_read_b128 v[24:27], v69 offset:28672
	v_add_f32_e32 v70, v110, v111
	v_add_f32_e32 v72, v112, v113
	v_pk_mul_f32 v[38:39], v[78:79], v[108:109] op_sel_hi:[1,0]
	v_add_f32_dpp v70, v70, v70 row_ror:8 row_mask:0xf bank_mask:0xf bound_ctrl:1
	v_add_f32_dpp v72, v72, v72 row_ror:8 row_mask:0xf bank_mask:0xf bound_ctrl:1
	v_pk_mul_f32 v[82:83], v[80:81], v[108:109] op_sel_hi:[1,0]
	v_add_f32_dpp v70, v70, v70 row_ror:4 row_mask:0xf bank_mask:0xf bound_ctrl:1
	v_add_f32_dpp v72, v72, v72 row_ror:4 row_mask:0xf bank_mask:0xf bound_ctrl:1
	v_pk_mul_f32 v[116:117], v[78:79], v[108:109] op_sel:[0,1] op_sel_hi:[1,1]
	v_add_f32_dpp v70, v70, v70 row_ror:2 row_mask:0xf bank_mask:0xf bound_ctrl:1
	v_add_f32_dpp v72, v72, v72 row_ror:2 row_mask:0xf bank_mask:0xf bound_ctrl:1
	v_pk_mul_f32 v[114:115], v[80:81], v[108:109] op_sel:[0,1] op_sel_hi:[1,1]
	v_add_f32_dpp v70, v70, v70 row_ror:1 row_mask:0xf bank_mask:0xf bound_ctrl:1
	v_add_f32_dpp v72, v72, v72 row_ror:1 row_mask:0xf bank_mask:0xf bound_ctrl:1
	v_pk_fma_f32 v[38:39], v[0:1], v[30:31], v[38:39]
	v_pk_fma_f32 v[82:83], v[2:3], v[32:33], v[82:83]
	v_pk_fma_f32 v[116:117], v[4:5], v[30:31], v[116:117]
	v_pk_fma_f32 v[114:115], v[6:7], v[32:33], v[114:115]
	v_pk_fma_f32 v[0:1], v[74:75], v[70:71], v[38:39] op_sel_hi:[1,0,1]
	v_pk_fma_f32 v[2:3], v[76:77], v[70:71], v[82:83] op_sel_hi:[1,0,1]
	v_pk_fma_f32 v[4:5], v[74:75], v[72:73], v[116:117] op_sel_hi:[1,0,1]
	v_pk_fma_f32 v[6:7], v[76:77], v[72:73], v[114:115] op_sel_hi:[1,0,1]
	v_pk_mul_f32 v[110:111], v[2:3], v[106:107]
	v_pk_mul_f32 v[112:113], v[6:7], v[106:107]
	v_pk_fma_f32 v[110:111], v[0:1], v[104:105], v[110:111]
	v_pk_fma_f32 v[112:113], v[4:5], v[104:105], v[112:113]
	v_add_f32_e32 v110, v110, v111
	v_add_f32_e32 v112, v112, v113
	ds_write_b32 v119, v110 offset:2048
	ds_write_b32 v119, v112 offset:2112
	s_waitcnt lgkmcnt(2)
	v_pk_mul_f32 v[110:111], v[2:3], v[14:15]
	v_pk_mul_f32 v[112:113], v[6:7], v[14:15]
	v_pk_fma_f32 v[110:111], v[0:1], v[12:13], v[110:111]
	v_pk_fma_f32 v[112:113], v[4:5], v[12:13], v[112:113]
	ds_read_b128 v[34:37], v69 offset:29440
	ds_read_b128 v[78:81], v69 offset:29952
	ds_read_b64 v[108:109], v118 offset:30464
	ds_read_b128 v[30:33], v69 offset:29184
	ds_read_b128 v[74:77], v69 offset:29696
	ds_read_b128 v[104:107], v69 offset:30208
	v_add_f32_e32 v70, v110, v111
	v_add_f32_e32 v72, v112, v113
	v_pk_mul_f32 v[38:39], v[20:21], v[28:29] op_sel_hi:[1,0]
	v_add_f32_dpp v70, v70, v70 row_ror:8 row_mask:0xf bank_mask:0xf bound_ctrl:1
	v_add_f32_dpp v72, v72, v72 row_ror:8 row_mask:0xf bank_mask:0xf bound_ctrl:1
	v_pk_mul_f32 v[82:83], v[22:23], v[28:29] op_sel_hi:[1,0]
	v_add_f32_dpp v70, v70, v70 row_ror:4 row_mask:0xf bank_mask:0xf bound_ctrl:1
	v_add_f32_dpp v72, v72, v72 row_ror:4 row_mask:0xf bank_mask:0xf bound_ctrl:1
	v_pk_mul_f32 v[116:117], v[20:21], v[28:29] op_sel:[0,1] op_sel_hi:[1,1]
	v_add_f32_dpp v70, v70, v70 row_ror:2 row_mask:0xf bank_mask:0xf bound_ctrl:1
	v_add_f32_dpp v72, v72, v72 row_ror:2 row_mask:0xf bank_mask:0xf bound_ctrl:1
	v_pk_mul_f32 v[114:115], v[22:23], v[28:29] op_sel:[0,1] op_sel_hi:[1,1]
	v_add_f32_dpp v70, v70, v70 row_ror:1 row_mask:0xf bank_mask:0xf bound_ctrl:1
	v_add_f32_dpp v72, v72, v72 row_ror:1 row_mask:0xf bank_mask:0xf bound_ctrl:1
	v_pk_fma_f32 v[38:39], v[0:1], v[8:9], v[38:39]
	v_pk_fma_f32 v[82:83], v[2:3], v[10:11], v[82:83]
	v_pk_fma_f32 v[116:117], v[4:5], v[8:9], v[116:117]
	v_pk_fma_f32 v[114:115], v[6:7], v[10:11], v[114:115]
	v_pk_fma_f32 v[0:1], v[16:17], v[70:71], v[38:39] op_sel_hi:[1,0,1]
	v_pk_fma_f32 v[2:3], v[18:19], v[70:71], v[82:83] op_sel_hi:[1,0,1]
	v_pk_fma_f32 v[4:5], v[16:17], v[72:73], v[116:117] op_sel_hi:[1,0,1]
	v_pk_fma_f32 v[6:7], v[18:19], v[72:73], v[114:115] op_sel_hi:[1,0,1]
	v_pk_mul_f32 v[110:111], v[2:3], v[26:27]
	v_pk_mul_f32 v[112:113], v[6:7], v[26:27]
	v_pk_fma_f32 v[110:111], v[0:1], v[24:25], v[110:111]
	v_pk_fma_f32 v[112:113], v[4:5], v[24:25], v[112:113]
	v_add_f32_e32 v110, v110, v111
	v_add_f32_e32 v112, v112, v113
	ds_write_b32 v119, v110 offset:4096
	ds_write_b32 v119, v112 offset:4160
	s_waitcnt lgkmcnt(2)
	v_pk_mul_f32 v[110:111], v[2:3], v[36:37]
	v_pk_mul_f32 v[112:113], v[6:7], v[36:37]
	v_pk_fma_f32 v[110:111], v[0:1], v[34:35], v[110:111]
	v_pk_fma_f32 v[112:113], v[4:5], v[34:35], v[112:113]
	ds_read_b128 v[12:15], v69 offset:30976
	ds_read_b128 v[20:23], v69 offset:31488
	ds_read_b64 v[28:29], v118 offset:32000
	ds_read_b128 v[8:11], v69 offset:30720
	ds_read_b128 v[16:19], v69 offset:31232
	ds_read_b128 v[24:27], v69 offset:31744
	v_add_f32_e32 v70, v110, v111
	v_add_f32_e32 v72, v112, v113
	v_pk_mul_f32 v[38:39], v[78:79], v[108:109] op_sel_hi:[1,0]
	v_add_f32_dpp v70, v70, v70 row_ror:8 row_mask:0xf bank_mask:0xf bound_ctrl:1
	v_add_f32_dpp v72, v72, v72 row_ror:8 row_mask:0xf bank_mask:0xf bound_ctrl:1
	v_pk_mul_f32 v[82:83], v[80:81], v[108:109] op_sel_hi:[1,0]
	v_add_f32_dpp v70, v70, v70 row_ror:4 row_mask:0xf bank_mask:0xf bound_ctrl:1
	v_add_f32_dpp v72, v72, v72 row_ror:4 row_mask:0xf bank_mask:0xf bound_ctrl:1
	v_pk_mul_f32 v[116:117], v[78:79], v[108:109] op_sel:[0,1] op_sel_hi:[1,1]
	v_add_f32_dpp v70, v70, v70 row_ror:2 row_mask:0xf bank_mask:0xf bound_ctrl:1
	v_add_f32_dpp v72, v72, v72 row_ror:2 row_mask:0xf bank_mask:0xf bound_ctrl:1
	v_pk_mul_f32 v[114:115], v[80:81], v[108:109] op_sel:[0,1] op_sel_hi:[1,1]
	v_add_f32_dpp v70, v70, v70 row_ror:1 row_mask:0xf bank_mask:0xf bound_ctrl:1
	v_add_f32_dpp v72, v72, v72 row_ror:1 row_mask:0xf bank_mask:0xf bound_ctrl:1
	v_pk_fma_f32 v[38:39], v[0:1], v[30:31], v[38:39]
	v_pk_fma_f32 v[82:83], v[2:3], v[32:33], v[82:83]
	v_pk_fma_f32 v[116:117], v[4:5], v[30:31], v[116:117]
	v_pk_fma_f32 v[114:115], v[6:7], v[32:33], v[114:115]
	v_pk_fma_f32 v[0:1], v[74:75], v[70:71], v[38:39] op_sel_hi:[1,0,1]
	v_pk_fma_f32 v[2:3], v[76:77], v[70:71], v[82:83] op_sel_hi:[1,0,1]
	v_pk_fma_f32 v[4:5], v[74:75], v[72:73], v[116:117] op_sel_hi:[1,0,1]
	v_pk_fma_f32 v[6:7], v[76:77], v[72:73], v[114:115] op_sel_hi:[1,0,1]
	v_pk_mul_f32 v[110:111], v[2:3], v[106:107]
	v_pk_mul_f32 v[112:113], v[6:7], v[106:107]
	v_pk_fma_f32 v[110:111], v[0:1], v[104:105], v[110:111]
	v_pk_fma_f32 v[112:113], v[4:5], v[104:105], v[112:113]
	v_add_f32_e32 v110, v110, v111
	v_add_f32_e32 v112, v112, v113
	ds_write_b32 v119, v110 offset:6144
	ds_write_b32 v119, v112 offset:6208
	s_waitcnt lgkmcnt(2)
	v_pk_mul_f32 v[110:111], v[2:3], v[14:15]
	v_pk_mul_f32 v[112:113], v[6:7], v[14:15]
	v_pk_fma_f32 v[110:111], v[0:1], v[12:13], v[110:111]
	v_pk_fma_f32 v[112:113], v[4:5], v[12:13], v[112:113]
	ds_read_b128 v[34:37], v69 offset:32512
	ds_read_b128 v[78:81], v69 offset:33024
	ds_read_b64 v[108:109], v118 offset:33536
	ds_read_b128 v[30:33], v69 offset:32256
	ds_read_b128 v[74:77], v69 offset:32768
	ds_read_b128 v[104:107], v69 offset:33280
	v_add_f32_e32 v70, v110, v111
	v_add_f32_e32 v72, v112, v113
	v_pk_mul_f32 v[38:39], v[20:21], v[28:29] op_sel_hi:[1,0]
	v_add_f32_dpp v70, v70, v70 row_ror:8 row_mask:0xf bank_mask:0xf bound_ctrl:1
	v_add_f32_dpp v72, v72, v72 row_ror:8 row_mask:0xf bank_mask:0xf bound_ctrl:1
	v_pk_mul_f32 v[82:83], v[22:23], v[28:29] op_sel_hi:[1,0]
	v_add_f32_dpp v70, v70, v70 row_ror:4 row_mask:0xf bank_mask:0xf bound_ctrl:1
	v_add_f32_dpp v72, v72, v72 row_ror:4 row_mask:0xf bank_mask:0xf bound_ctrl:1
	v_pk_mul_f32 v[116:117], v[20:21], v[28:29] op_sel:[0,1] op_sel_hi:[1,1]
	v_add_f32_dpp v70, v70, v70 row_ror:2 row_mask:0xf bank_mask:0xf bound_ctrl:1
	v_add_f32_dpp v72, v72, v72 row_ror:2 row_mask:0xf bank_mask:0xf bound_ctrl:1
	v_pk_mul_f32 v[114:115], v[22:23], v[28:29] op_sel:[0,1] op_sel_hi:[1,1]
	v_add_f32_dpp v70, v70, v70 row_ror:1 row_mask:0xf bank_mask:0xf bound_ctrl:1
	v_add_f32_dpp v72, v72, v72 row_ror:1 row_mask:0xf bank_mask:0xf bound_ctrl:1
	v_pk_fma_f32 v[38:39], v[0:1], v[8:9], v[38:39]
	v_pk_fma_f32 v[82:83], v[2:3], v[10:11], v[82:83]
	v_pk_fma_f32 v[116:117], v[4:5], v[8:9], v[116:117]
	v_pk_fma_f32 v[114:115], v[6:7], v[10:11], v[114:115]
	v_pk_fma_f32 v[0:1], v[16:17], v[70:71], v[38:39] op_sel_hi:[1,0,1]
	v_pk_fma_f32 v[2:3], v[18:19], v[70:71], v[82:83] op_sel_hi:[1,0,1]
	v_pk_fma_f32 v[4:5], v[16:17], v[72:73], v[116:117] op_sel_hi:[1,0,1]
	v_pk_fma_f32 v[6:7], v[18:19], v[72:73], v[114:115] op_sel_hi:[1,0,1]
	v_pk_mul_f32 v[110:111], v[2:3], v[26:27]
	v_pk_mul_f32 v[112:113], v[6:7], v[26:27]
	v_pk_fma_f32 v[110:111], v[0:1], v[24:25], v[110:111]
	v_pk_fma_f32 v[112:113], v[4:5], v[24:25], v[112:113]
	v_add_f32_e32 v110, v110, v111
	v_add_f32_e32 v112, v112, v113
	ds_write_b32 v119, v110 offset:8192
	ds_write_b32 v119, v112 offset:8256
	s_waitcnt lgkmcnt(2)
	v_pk_mul_f32 v[110:111], v[2:3], v[36:37]
	v_pk_mul_f32 v[112:113], v[6:7], v[36:37]
	v_pk_fma_f32 v[110:111], v[0:1], v[34:35], v[110:111]
	v_pk_fma_f32 v[112:113], v[4:5], v[34:35], v[112:113]
	ds_read_b128 v[12:15], v69 offset:34048
	ds_read_b128 v[20:23], v69 offset:34560
	ds_read_b64 v[28:29], v118 offset:35072
	ds_read_b128 v[8:11], v69 offset:33792
	ds_read_b128 v[16:19], v69 offset:34304
	ds_read_b128 v[24:27], v69 offset:34816
	v_add_f32_e32 v70, v110, v111
	v_add_f32_e32 v72, v112, v113
	v_pk_mul_f32 v[38:39], v[78:79], v[108:109] op_sel_hi:[1,0]
	v_add_f32_dpp v70, v70, v70 row_ror:8 row_mask:0xf bank_mask:0xf bound_ctrl:1
	v_add_f32_dpp v72, v72, v72 row_ror:8 row_mask:0xf bank_mask:0xf bound_ctrl:1
	v_pk_mul_f32 v[82:83], v[80:81], v[108:109] op_sel_hi:[1,0]
	v_add_f32_dpp v70, v70, v70 row_ror:4 row_mask:0xf bank_mask:0xf bound_ctrl:1
	v_add_f32_dpp v72, v72, v72 row_ror:4 row_mask:0xf bank_mask:0xf bound_ctrl:1
	v_pk_mul_f32 v[116:117], v[78:79], v[108:109] op_sel:[0,1] op_sel_hi:[1,1]
	v_add_f32_dpp v70, v70, v70 row_ror:2 row_mask:0xf bank_mask:0xf bound_ctrl:1
	v_add_f32_dpp v72, v72, v72 row_ror:2 row_mask:0xf bank_mask:0xf bound_ctrl:1
	v_pk_mul_f32 v[114:115], v[80:81], v[108:109] op_sel:[0,1] op_sel_hi:[1,1]
	v_add_f32_dpp v70, v70, v70 row_ror:1 row_mask:0xf bank_mask:0xf bound_ctrl:1
	v_add_f32_dpp v72, v72, v72 row_ror:1 row_mask:0xf bank_mask:0xf bound_ctrl:1
	v_pk_fma_f32 v[38:39], v[0:1], v[30:31], v[38:39]
	v_pk_fma_f32 v[82:83], v[2:3], v[32:33], v[82:83]
	v_pk_fma_f32 v[116:117], v[4:5], v[30:31], v[116:117]
	v_pk_fma_f32 v[114:115], v[6:7], v[32:33], v[114:115]
	v_pk_fma_f32 v[0:1], v[74:75], v[70:71], v[38:39] op_sel_hi:[1,0,1]
	v_pk_fma_f32 v[2:3], v[76:77], v[70:71], v[82:83] op_sel_hi:[1,0,1]
	v_pk_fma_f32 v[4:5], v[74:75], v[72:73], v[116:117] op_sel_hi:[1,0,1]
	v_pk_fma_f32 v[6:7], v[76:77], v[72:73], v[114:115] op_sel_hi:[1,0,1]
	v_pk_mul_f32 v[110:111], v[2:3], v[106:107]
	v_pk_mul_f32 v[112:113], v[6:7], v[106:107]
	v_pk_fma_f32 v[110:111], v[0:1], v[104:105], v[110:111]
	v_pk_fma_f32 v[112:113], v[4:5], v[104:105], v[112:113]
	v_add_f32_e32 v110, v110, v111
	v_add_f32_e32 v112, v112, v113
	ds_write_b32 v119, v110 offset:10240
	ds_write_b32 v119, v112 offset:10304
	s_waitcnt lgkmcnt(2)
	v_pk_mul_f32 v[110:111], v[2:3], v[14:15]
	v_pk_mul_f32 v[112:113], v[6:7], v[14:15]
	v_pk_fma_f32 v[110:111], v[0:1], v[12:13], v[110:111]
	v_pk_fma_f32 v[112:113], v[4:5], v[12:13], v[112:113]
	ds_read_b128 v[34:37], v69 offset:35584
	ds_read_b128 v[78:81], v69 offset:36096
	ds_read_b64 v[108:109], v118 offset:36608
	ds_read_b128 v[30:33], v69 offset:35328
	ds_read_b128 v[74:77], v69 offset:35840
	ds_read_b128 v[104:107], v69 offset:36352
	v_add_f32_e32 v70, v110, v111
	v_add_f32_e32 v72, v112, v113
	v_pk_mul_f32 v[38:39], v[20:21], v[28:29] op_sel_hi:[1,0]
	v_add_f32_dpp v70, v70, v70 row_ror:8 row_mask:0xf bank_mask:0xf bound_ctrl:1
	v_add_f32_dpp v72, v72, v72 row_ror:8 row_mask:0xf bank_mask:0xf bound_ctrl:1
	v_pk_mul_f32 v[82:83], v[22:23], v[28:29] op_sel_hi:[1,0]
	v_add_f32_dpp v70, v70, v70 row_ror:4 row_mask:0xf bank_mask:0xf bound_ctrl:1
	v_add_f32_dpp v72, v72, v72 row_ror:4 row_mask:0xf bank_mask:0xf bound_ctrl:1
	v_pk_mul_f32 v[116:117], v[20:21], v[28:29] op_sel:[0,1] op_sel_hi:[1,1]
	v_add_f32_dpp v70, v70, v70 row_ror:2 row_mask:0xf bank_mask:0xf bound_ctrl:1
	v_add_f32_dpp v72, v72, v72 row_ror:2 row_mask:0xf bank_mask:0xf bound_ctrl:1
	v_pk_mul_f32 v[114:115], v[22:23], v[28:29] op_sel:[0,1] op_sel_hi:[1,1]
	v_add_f32_dpp v70, v70, v70 row_ror:1 row_mask:0xf bank_mask:0xf bound_ctrl:1
	v_add_f32_dpp v72, v72, v72 row_ror:1 row_mask:0xf bank_mask:0xf bound_ctrl:1
	v_pk_fma_f32 v[38:39], v[0:1], v[8:9], v[38:39]
	v_pk_fma_f32 v[82:83], v[2:3], v[10:11], v[82:83]
	v_pk_fma_f32 v[116:117], v[4:5], v[8:9], v[116:117]
	v_pk_fma_f32 v[114:115], v[6:7], v[10:11], v[114:115]
	v_pk_fma_f32 v[0:1], v[16:17], v[70:71], v[38:39] op_sel_hi:[1,0,1]
	v_pk_fma_f32 v[2:3], v[18:19], v[70:71], v[82:83] op_sel_hi:[1,0,1]
	v_pk_fma_f32 v[4:5], v[16:17], v[72:73], v[116:117] op_sel_hi:[1,0,1]
	v_pk_fma_f32 v[6:7], v[18:19], v[72:73], v[114:115] op_sel_hi:[1,0,1]
	v_pk_mul_f32 v[110:111], v[2:3], v[26:27]
	v_pk_mul_f32 v[112:113], v[6:7], v[26:27]
	v_pk_fma_f32 v[110:111], v[0:1], v[24:25], v[110:111]
	v_pk_fma_f32 v[112:113], v[4:5], v[24:25], v[112:113]
	v_add_f32_e32 v110, v110, v111
	v_add_f32_e32 v112, v112, v113
	ds_write_b32 v119, v110 offset:12288
	ds_write_b32 v119, v112 offset:12352
	s_waitcnt lgkmcnt(2)
	v_pk_mul_f32 v[110:111], v[2:3], v[36:37]
	v_pk_mul_f32 v[112:113], v[6:7], v[36:37]
	v_pk_fma_f32 v[110:111], v[0:1], v[34:35], v[110:111]
	v_pk_fma_f32 v[112:113], v[4:5], v[34:35], v[112:113]
	ds_read_b128 v[12:15], v69 offset:37120
	ds_read_b128 v[20:23], v69 offset:37632
	ds_read_b64 v[28:29], v118 offset:38144
	ds_read_b128 v[8:11], v69 offset:36864
	ds_read_b128 v[16:19], v69 offset:37376
	ds_read_b128 v[24:27], v69 offset:37888
	v_add_f32_e32 v70, v110, v111
	v_add_f32_e32 v72, v112, v113
	v_pk_mul_f32 v[38:39], v[78:79], v[108:109] op_sel_hi:[1,0]
	v_add_f32_dpp v70, v70, v70 row_ror:8 row_mask:0xf bank_mask:0xf bound_ctrl:1
	v_add_f32_dpp v72, v72, v72 row_ror:8 row_mask:0xf bank_mask:0xf bound_ctrl:1
	v_pk_mul_f32 v[82:83], v[80:81], v[108:109] op_sel_hi:[1,0]
	v_add_f32_dpp v70, v70, v70 row_ror:4 row_mask:0xf bank_mask:0xf bound_ctrl:1
	v_add_f32_dpp v72, v72, v72 row_ror:4 row_mask:0xf bank_mask:0xf bound_ctrl:1
	v_pk_mul_f32 v[116:117], v[78:79], v[108:109] op_sel:[0,1] op_sel_hi:[1,1]
	v_add_f32_dpp v70, v70, v70 row_ror:2 row_mask:0xf bank_mask:0xf bound_ctrl:1
	v_add_f32_dpp v72, v72, v72 row_ror:2 row_mask:0xf bank_mask:0xf bound_ctrl:1
	v_pk_mul_f32 v[114:115], v[80:81], v[108:109] op_sel:[0,1] op_sel_hi:[1,1]
	v_add_f32_dpp v70, v70, v70 row_ror:1 row_mask:0xf bank_mask:0xf bound_ctrl:1
	v_add_f32_dpp v72, v72, v72 row_ror:1 row_mask:0xf bank_mask:0xf bound_ctrl:1
	v_pk_fma_f32 v[38:39], v[0:1], v[30:31], v[38:39]
	v_pk_fma_f32 v[82:83], v[2:3], v[32:33], v[82:83]
	v_pk_fma_f32 v[116:117], v[4:5], v[30:31], v[116:117]
	v_pk_fma_f32 v[114:115], v[6:7], v[32:33], v[114:115]
	v_pk_fma_f32 v[0:1], v[74:75], v[70:71], v[38:39] op_sel_hi:[1,0,1]
	v_pk_fma_f32 v[2:3], v[76:77], v[70:71], v[82:83] op_sel_hi:[1,0,1]
	v_pk_fma_f32 v[4:5], v[74:75], v[72:73], v[116:117] op_sel_hi:[1,0,1]
	v_pk_fma_f32 v[6:7], v[76:77], v[72:73], v[114:115] op_sel_hi:[1,0,1]
	v_pk_mul_f32 v[110:111], v[2:3], v[106:107]
	v_pk_mul_f32 v[112:113], v[6:7], v[106:107]
	v_pk_fma_f32 v[110:111], v[0:1], v[104:105], v[110:111]
	v_pk_fma_f32 v[112:113], v[4:5], v[104:105], v[112:113]
	v_add_f32_e32 v110, v110, v111
	v_add_f32_e32 v112, v112, v113
	ds_write_b32 v119, v110 offset:14336
	ds_write_b32 v119, v112 offset:14400
	s_waitcnt lgkmcnt(2)
	v_pk_mul_f32 v[110:111], v[2:3], v[14:15]
	v_pk_mul_f32 v[112:113], v[6:7], v[14:15]
	v_pk_fma_f32 v[110:111], v[0:1], v[12:13], v[110:111]
	v_pk_fma_f32 v[112:113], v[4:5], v[12:13], v[112:113]
	ds_read_b128 v[34:37], v69 offset:38656
	ds_read_b128 v[78:81], v69 offset:39168
	ds_read_b64 v[108:109], v118 offset:39680
	ds_read_b128 v[30:33], v69 offset:38400
	ds_read_b128 v[74:77], v69 offset:38912
	ds_read_b128 v[104:107], v69 offset:39424
	v_add_f32_e32 v70, v110, v111
	v_add_f32_e32 v72, v112, v113
	v_pk_mul_f32 v[38:39], v[20:21], v[28:29] op_sel_hi:[1,0]
	v_add_f32_dpp v70, v70, v70 row_ror:8 row_mask:0xf bank_mask:0xf bound_ctrl:1
	v_add_f32_dpp v72, v72, v72 row_ror:8 row_mask:0xf bank_mask:0xf bound_ctrl:1
	v_pk_mul_f32 v[82:83], v[22:23], v[28:29] op_sel_hi:[1,0]
	v_add_f32_dpp v70, v70, v70 row_ror:4 row_mask:0xf bank_mask:0xf bound_ctrl:1
	v_add_f32_dpp v72, v72, v72 row_ror:4 row_mask:0xf bank_mask:0xf bound_ctrl:1
	v_pk_mul_f32 v[116:117], v[20:21], v[28:29] op_sel:[0,1] op_sel_hi:[1,1]
	v_add_f32_dpp v70, v70, v70 row_ror:2 row_mask:0xf bank_mask:0xf bound_ctrl:1
	v_add_f32_dpp v72, v72, v72 row_ror:2 row_mask:0xf bank_mask:0xf bound_ctrl:1
	v_pk_mul_f32 v[114:115], v[22:23], v[28:29] op_sel:[0,1] op_sel_hi:[1,1]
	v_add_f32_dpp v70, v70, v70 row_ror:1 row_mask:0xf bank_mask:0xf bound_ctrl:1
	v_add_f32_dpp v72, v72, v72 row_ror:1 row_mask:0xf bank_mask:0xf bound_ctrl:1
	v_pk_fma_f32 v[38:39], v[0:1], v[8:9], v[38:39]
	v_pk_fma_f32 v[82:83], v[2:3], v[10:11], v[82:83]
	v_pk_fma_f32 v[116:117], v[4:5], v[8:9], v[116:117]
	v_pk_fma_f32 v[114:115], v[6:7], v[10:11], v[114:115]
	v_pk_fma_f32 v[0:1], v[16:17], v[70:71], v[38:39] op_sel_hi:[1,0,1]
	v_pk_fma_f32 v[2:3], v[18:19], v[70:71], v[82:83] op_sel_hi:[1,0,1]
	v_pk_fma_f32 v[4:5], v[16:17], v[72:73], v[116:117] op_sel_hi:[1,0,1]
	v_pk_fma_f32 v[6:7], v[18:19], v[72:73], v[114:115] op_sel_hi:[1,0,1]
	v_pk_mul_f32 v[110:111], v[2:3], v[26:27]
	v_pk_mul_f32 v[112:113], v[6:7], v[26:27]
	v_pk_fma_f32 v[110:111], v[0:1], v[24:25], v[110:111]
	v_pk_fma_f32 v[112:113], v[4:5], v[24:25], v[112:113]
	v_add_f32_e32 v110, v110, v111
	v_add_f32_e32 v112, v112, v113
	ds_write_b32 v119, v110 offset:16384
	ds_write_b32 v119, v112 offset:16448
	s_waitcnt lgkmcnt(2)
	v_pk_mul_f32 v[110:111], v[2:3], v[36:37]
	v_pk_mul_f32 v[112:113], v[6:7], v[36:37]
	v_pk_fma_f32 v[110:111], v[0:1], v[34:35], v[110:111]
	v_pk_fma_f32 v[112:113], v[4:5], v[34:35], v[112:113]
	ds_read_b128 v[12:15], v69 offset:40192
	ds_read_b128 v[20:23], v69 offset:40704
	ds_read_b64 v[28:29], v118 offset:41216
	ds_read_b128 v[8:11], v69 offset:39936
	ds_read_b128 v[16:19], v69 offset:40448
	ds_read_b128 v[24:27], v69 offset:40960
	v_add_f32_e32 v70, v110, v111
	v_add_f32_e32 v72, v112, v113
	v_pk_mul_f32 v[38:39], v[78:79], v[108:109] op_sel_hi:[1,0]
	v_add_f32_dpp v70, v70, v70 row_ror:8 row_mask:0xf bank_mask:0xf bound_ctrl:1
	v_add_f32_dpp v72, v72, v72 row_ror:8 row_mask:0xf bank_mask:0xf bound_ctrl:1
	v_pk_mul_f32 v[82:83], v[80:81], v[108:109] op_sel_hi:[1,0]
	v_add_f32_dpp v70, v70, v70 row_ror:4 row_mask:0xf bank_mask:0xf bound_ctrl:1
	v_add_f32_dpp v72, v72, v72 row_ror:4 row_mask:0xf bank_mask:0xf bound_ctrl:1
	v_pk_mul_f32 v[116:117], v[78:79], v[108:109] op_sel:[0,1] op_sel_hi:[1,1]
	v_add_f32_dpp v70, v70, v70 row_ror:2 row_mask:0xf bank_mask:0xf bound_ctrl:1
	v_add_f32_dpp v72, v72, v72 row_ror:2 row_mask:0xf bank_mask:0xf bound_ctrl:1
	v_pk_mul_f32 v[114:115], v[80:81], v[108:109] op_sel:[0,1] op_sel_hi:[1,1]
	v_add_f32_dpp v70, v70, v70 row_ror:1 row_mask:0xf bank_mask:0xf bound_ctrl:1
	v_add_f32_dpp v72, v72, v72 row_ror:1 row_mask:0xf bank_mask:0xf bound_ctrl:1
	v_pk_fma_f32 v[38:39], v[0:1], v[30:31], v[38:39]
	v_pk_fma_f32 v[82:83], v[2:3], v[32:33], v[82:83]
	v_pk_fma_f32 v[116:117], v[4:5], v[30:31], v[116:117]
	v_pk_fma_f32 v[114:115], v[6:7], v[32:33], v[114:115]
	v_pk_fma_f32 v[0:1], v[74:75], v[70:71], v[38:39] op_sel_hi:[1,0,1]
	v_pk_fma_f32 v[2:3], v[76:77], v[70:71], v[82:83] op_sel_hi:[1,0,1]
	v_pk_fma_f32 v[4:5], v[74:75], v[72:73], v[116:117] op_sel_hi:[1,0,1]
	v_pk_fma_f32 v[6:7], v[76:77], v[72:73], v[114:115] op_sel_hi:[1,0,1]
	v_pk_mul_f32 v[110:111], v[2:3], v[106:107]
	v_pk_mul_f32 v[112:113], v[6:7], v[106:107]
	v_pk_fma_f32 v[110:111], v[0:1], v[104:105], v[110:111]
	v_pk_fma_f32 v[112:113], v[4:5], v[104:105], v[112:113]
	v_add_f32_e32 v110, v110, v111
	v_add_f32_e32 v112, v112, v113
	ds_write_b32 v119, v110 offset:18432
	ds_write_b32 v119, v112 offset:18496
	s_waitcnt lgkmcnt(2)
	v_pk_mul_f32 v[110:111], v[2:3], v[14:15]
	v_pk_mul_f32 v[112:113], v[6:7], v[14:15]
	v_pk_fma_f32 v[110:111], v[0:1], v[12:13], v[110:111]
	v_pk_fma_f32 v[112:113], v[4:5], v[12:13], v[112:113]
	ds_read_b128 v[34:37], v69 offset:41728
	ds_read_b128 v[78:81], v69 offset:42240
	ds_read_b64 v[108:109], v118 offset:42752
	ds_read_b128 v[30:33], v69 offset:41472
	ds_read_b128 v[74:77], v69 offset:41984
	ds_read_b128 v[104:107], v69 offset:42496
	v_add_f32_e32 v70, v110, v111
	v_add_f32_e32 v72, v112, v113
	v_pk_mul_f32 v[38:39], v[20:21], v[28:29] op_sel_hi:[1,0]
	v_add_f32_dpp v70, v70, v70 row_ror:8 row_mask:0xf bank_mask:0xf bound_ctrl:1
	v_add_f32_dpp v72, v72, v72 row_ror:8 row_mask:0xf bank_mask:0xf bound_ctrl:1
	v_pk_mul_f32 v[82:83], v[22:23], v[28:29] op_sel_hi:[1,0]
	v_add_f32_dpp v70, v70, v70 row_ror:4 row_mask:0xf bank_mask:0xf bound_ctrl:1
	v_add_f32_dpp v72, v72, v72 row_ror:4 row_mask:0xf bank_mask:0xf bound_ctrl:1
	v_pk_mul_f32 v[116:117], v[20:21], v[28:29] op_sel:[0,1] op_sel_hi:[1,1]
	v_add_f32_dpp v70, v70, v70 row_ror:2 row_mask:0xf bank_mask:0xf bound_ctrl:1
	v_add_f32_dpp v72, v72, v72 row_ror:2 row_mask:0xf bank_mask:0xf bound_ctrl:1
	v_pk_mul_f32 v[114:115], v[22:23], v[28:29] op_sel:[0,1] op_sel_hi:[1,1]
	v_add_f32_dpp v70, v70, v70 row_ror:1 row_mask:0xf bank_mask:0xf bound_ctrl:1
	v_add_f32_dpp v72, v72, v72 row_ror:1 row_mask:0xf bank_mask:0xf bound_ctrl:1
	v_pk_fma_f32 v[38:39], v[0:1], v[8:9], v[38:39]
	v_pk_fma_f32 v[82:83], v[2:3], v[10:11], v[82:83]
	v_pk_fma_f32 v[116:117], v[4:5], v[8:9], v[116:117]
	v_pk_fma_f32 v[114:115], v[6:7], v[10:11], v[114:115]
	v_pk_fma_f32 v[0:1], v[16:17], v[70:71], v[38:39] op_sel_hi:[1,0,1]
	v_pk_fma_f32 v[2:3], v[18:19], v[70:71], v[82:83] op_sel_hi:[1,0,1]
	v_pk_fma_f32 v[4:5], v[16:17], v[72:73], v[116:117] op_sel_hi:[1,0,1]
	v_pk_fma_f32 v[6:7], v[18:19], v[72:73], v[114:115] op_sel_hi:[1,0,1]
	v_pk_mul_f32 v[110:111], v[2:3], v[26:27]
	v_pk_mul_f32 v[112:113], v[6:7], v[26:27]
	v_pk_fma_f32 v[110:111], v[0:1], v[24:25], v[110:111]
	v_pk_fma_f32 v[112:113], v[4:5], v[24:25], v[112:113]
	v_add_f32_e32 v110, v110, v111
	v_add_f32_e32 v112, v112, v113
	ds_write_b32 v119, v110 offset:20480
	ds_write_b32 v119, v112 offset:20544
	s_waitcnt lgkmcnt(2)
	v_pk_mul_f32 v[110:111], v[2:3], v[36:37]
	v_pk_mul_f32 v[112:113], v[6:7], v[36:37]
	v_pk_fma_f32 v[110:111], v[0:1], v[34:35], v[110:111]
	v_pk_fma_f32 v[112:113], v[4:5], v[34:35], v[112:113]
	ds_read_b128 v[12:15], v69 offset:43264
	ds_read_b128 v[20:23], v69 offset:43776
	ds_read_b64 v[28:29], v118 offset:44288
	ds_read_b128 v[8:11], v69 offset:43008
	ds_read_b128 v[16:19], v69 offset:43520
	ds_read_b128 v[24:27], v69 offset:44032
	v_add_f32_e32 v70, v110, v111
	v_add_f32_e32 v72, v112, v113
	v_pk_mul_f32 v[38:39], v[78:79], v[108:109] op_sel_hi:[1,0]
	v_add_f32_dpp v70, v70, v70 row_ror:8 row_mask:0xf bank_mask:0xf bound_ctrl:1
	v_add_f32_dpp v72, v72, v72 row_ror:8 row_mask:0xf bank_mask:0xf bound_ctrl:1
	v_pk_mul_f32 v[82:83], v[80:81], v[108:109] op_sel_hi:[1,0]
	v_add_f32_dpp v70, v70, v70 row_ror:4 row_mask:0xf bank_mask:0xf bound_ctrl:1
	v_add_f32_dpp v72, v72, v72 row_ror:4 row_mask:0xf bank_mask:0xf bound_ctrl:1
	v_pk_mul_f32 v[116:117], v[78:79], v[108:109] op_sel:[0,1] op_sel_hi:[1,1]
	v_add_f32_dpp v70, v70, v70 row_ror:2 row_mask:0xf bank_mask:0xf bound_ctrl:1
	v_add_f32_dpp v72, v72, v72 row_ror:2 row_mask:0xf bank_mask:0xf bound_ctrl:1
	v_pk_mul_f32 v[114:115], v[80:81], v[108:109] op_sel:[0,1] op_sel_hi:[1,1]
	v_add_f32_dpp v70, v70, v70 row_ror:1 row_mask:0xf bank_mask:0xf bound_ctrl:1
	v_add_f32_dpp v72, v72, v72 row_ror:1 row_mask:0xf bank_mask:0xf bound_ctrl:1
	v_pk_fma_f32 v[38:39], v[0:1], v[30:31], v[38:39]
	v_pk_fma_f32 v[82:83], v[2:3], v[32:33], v[82:83]
	v_pk_fma_f32 v[116:117], v[4:5], v[30:31], v[116:117]
	v_pk_fma_f32 v[114:115], v[6:7], v[32:33], v[114:115]
	v_pk_fma_f32 v[0:1], v[74:75], v[70:71], v[38:39] op_sel_hi:[1,0,1]
	v_pk_fma_f32 v[2:3], v[76:77], v[70:71], v[82:83] op_sel_hi:[1,0,1]
	v_pk_fma_f32 v[4:5], v[74:75], v[72:73], v[116:117] op_sel_hi:[1,0,1]
	v_pk_fma_f32 v[6:7], v[76:77], v[72:73], v[114:115] op_sel_hi:[1,0,1]
	v_pk_mul_f32 v[110:111], v[2:3], v[106:107]
	v_pk_mul_f32 v[112:113], v[6:7], v[106:107]
	v_pk_fma_f32 v[110:111], v[0:1], v[104:105], v[110:111]
	v_pk_fma_f32 v[112:113], v[4:5], v[104:105], v[112:113]
	v_add_f32_e32 v110, v110, v111
	v_add_f32_e32 v112, v112, v113
	ds_write_b32 v119, v110 offset:22528
	ds_write_b32 v119, v112 offset:22592
	s_waitcnt lgkmcnt(2)
	v_pk_mul_f32 v[110:111], v[2:3], v[14:15]
	v_pk_mul_f32 v[112:113], v[6:7], v[14:15]
	v_pk_fma_f32 v[110:111], v[0:1], v[12:13], v[110:111]
	v_pk_fma_f32 v[112:113], v[4:5], v[12:13], v[112:113]
	ds_read_b128 v[34:37], v69 offset:44800
	ds_read_b128 v[78:81], v69 offset:45312
	ds_read_b64 v[108:109], v118 offset:45824
	ds_read_b128 v[30:33], v69 offset:44544
	ds_read_b128 v[74:77], v69 offset:45056
	ds_read_b128 v[104:107], v69 offset:45568
	v_add_f32_e32 v70, v110, v111
	v_add_f32_e32 v72, v112, v113
	v_pk_mul_f32 v[38:39], v[20:21], v[28:29] op_sel_hi:[1,0]
	v_add_f32_dpp v70, v70, v70 row_ror:8 row_mask:0xf bank_mask:0xf bound_ctrl:1
	v_add_f32_dpp v72, v72, v72 row_ror:8 row_mask:0xf bank_mask:0xf bound_ctrl:1
	v_pk_mul_f32 v[82:83], v[22:23], v[28:29] op_sel_hi:[1,0]
	v_add_f32_dpp v70, v70, v70 row_ror:4 row_mask:0xf bank_mask:0xf bound_ctrl:1
	v_add_f32_dpp v72, v72, v72 row_ror:4 row_mask:0xf bank_mask:0xf bound_ctrl:1
	v_pk_mul_f32 v[116:117], v[20:21], v[28:29] op_sel:[0,1] op_sel_hi:[1,1]
	v_add_f32_dpp v70, v70, v70 row_ror:2 row_mask:0xf bank_mask:0xf bound_ctrl:1
	v_add_f32_dpp v72, v72, v72 row_ror:2 row_mask:0xf bank_mask:0xf bound_ctrl:1
	v_pk_mul_f32 v[114:115], v[22:23], v[28:29] op_sel:[0,1] op_sel_hi:[1,1]
	v_add_f32_dpp v70, v70, v70 row_ror:1 row_mask:0xf bank_mask:0xf bound_ctrl:1
	v_add_f32_dpp v72, v72, v72 row_ror:1 row_mask:0xf bank_mask:0xf bound_ctrl:1
	v_pk_fma_f32 v[38:39], v[0:1], v[8:9], v[38:39]
	v_pk_fma_f32 v[82:83], v[2:3], v[10:11], v[82:83]
	v_pk_fma_f32 v[116:117], v[4:5], v[8:9], v[116:117]
	v_pk_fma_f32 v[114:115], v[6:7], v[10:11], v[114:115]
	v_pk_fma_f32 v[0:1], v[16:17], v[70:71], v[38:39] op_sel_hi:[1,0,1]
	v_pk_fma_f32 v[2:3], v[18:19], v[70:71], v[82:83] op_sel_hi:[1,0,1]
	v_pk_fma_f32 v[4:5], v[16:17], v[72:73], v[116:117] op_sel_hi:[1,0,1]
	v_pk_fma_f32 v[6:7], v[18:19], v[72:73], v[114:115] op_sel_hi:[1,0,1]
	v_pk_mul_f32 v[110:111], v[2:3], v[26:27]
	v_pk_mul_f32 v[112:113], v[6:7], v[26:27]
	v_pk_fma_f32 v[110:111], v[0:1], v[24:25], v[110:111]
	v_pk_fma_f32 v[112:113], v[4:5], v[24:25], v[112:113]
	v_add_f32_e32 v110, v110, v111
	v_add_f32_e32 v112, v112, v113
	ds_write_b32 v119, v110 offset:24576
	ds_write_b32 v119, v112 offset:24640
	s_waitcnt lgkmcnt(2)
	v_pk_mul_f32 v[110:111], v[2:3], v[36:37]
	v_pk_mul_f32 v[112:113], v[6:7], v[36:37]
	v_pk_fma_f32 v[110:111], v[0:1], v[34:35], v[110:111]
	v_pk_fma_f32 v[112:113], v[4:5], v[34:35], v[112:113]
	ds_read_b128 v[12:15], v69 offset:46336
	ds_read_b128 v[20:23], v69 offset:46848
	ds_read_b64 v[28:29], v118 offset:47360
	ds_read_b128 v[8:11], v69 offset:46080
	ds_read_b128 v[16:19], v69 offset:46592
	ds_read_b128 v[24:27], v69 offset:47104
	v_add_f32_e32 v70, v110, v111
	v_add_f32_e32 v72, v112, v113
	v_pk_mul_f32 v[38:39], v[78:79], v[108:109] op_sel_hi:[1,0]
	v_add_f32_dpp v70, v70, v70 row_ror:8 row_mask:0xf bank_mask:0xf bound_ctrl:1
	v_add_f32_dpp v72, v72, v72 row_ror:8 row_mask:0xf bank_mask:0xf bound_ctrl:1
	v_pk_mul_f32 v[82:83], v[80:81], v[108:109] op_sel_hi:[1,0]
	v_add_f32_dpp v70, v70, v70 row_ror:4 row_mask:0xf bank_mask:0xf bound_ctrl:1
	v_add_f32_dpp v72, v72, v72 row_ror:4 row_mask:0xf bank_mask:0xf bound_ctrl:1
	v_pk_mul_f32 v[116:117], v[78:79], v[108:109] op_sel:[0,1] op_sel_hi:[1,1]
	v_add_f32_dpp v70, v70, v70 row_ror:2 row_mask:0xf bank_mask:0xf bound_ctrl:1
	v_add_f32_dpp v72, v72, v72 row_ror:2 row_mask:0xf bank_mask:0xf bound_ctrl:1
	v_pk_mul_f32 v[114:115], v[80:81], v[108:109] op_sel:[0,1] op_sel_hi:[1,1]
	v_add_f32_dpp v70, v70, v70 row_ror:1 row_mask:0xf bank_mask:0xf bound_ctrl:1
	v_add_f32_dpp v72, v72, v72 row_ror:1 row_mask:0xf bank_mask:0xf bound_ctrl:1
	v_pk_fma_f32 v[38:39], v[0:1], v[30:31], v[38:39]
	v_pk_fma_f32 v[82:83], v[2:3], v[32:33], v[82:83]
	v_pk_fma_f32 v[116:117], v[4:5], v[30:31], v[116:117]
	v_pk_fma_f32 v[114:115], v[6:7], v[32:33], v[114:115]
	v_pk_fma_f32 v[0:1], v[74:75], v[70:71], v[38:39] op_sel_hi:[1,0,1]
	v_pk_fma_f32 v[2:3], v[76:77], v[70:71], v[82:83] op_sel_hi:[1,0,1]
	v_pk_fma_f32 v[4:5], v[74:75], v[72:73], v[116:117] op_sel_hi:[1,0,1]
	v_pk_fma_f32 v[6:7], v[76:77], v[72:73], v[114:115] op_sel_hi:[1,0,1]
	v_pk_mul_f32 v[110:111], v[2:3], v[106:107]
	v_pk_mul_f32 v[112:113], v[6:7], v[106:107]
	v_pk_fma_f32 v[110:111], v[0:1], v[104:105], v[110:111]
	v_pk_fma_f32 v[112:113], v[4:5], v[104:105], v[112:113]
	v_add_f32_e32 v110, v110, v111
	v_add_f32_e32 v112, v112, v113
	ds_write_b32 v119, v110 offset:26624
	ds_write_b32 v119, v112 offset:26688
	s_waitcnt lgkmcnt(2)
	v_pk_mul_f32 v[110:111], v[2:3], v[14:15]
	v_pk_mul_f32 v[112:113], v[6:7], v[14:15]
	v_pk_fma_f32 v[110:111], v[0:1], v[12:13], v[110:111]
	v_pk_fma_f32 v[112:113], v[4:5], v[12:13], v[112:113]
	ds_read_b128 v[34:37], v69 offset:47872
	ds_read_b128 v[78:81], v69 offset:48384
	ds_read_b64 v[108:109], v118 offset:48896
	ds_read_b128 v[30:33], v69 offset:47616
	ds_read_b128 v[74:77], v69 offset:48128
	ds_read_b128 v[104:107], v69 offset:48640
	v_add_f32_e32 v70, v110, v111
	v_add_f32_e32 v72, v112, v113
	v_pk_mul_f32 v[38:39], v[20:21], v[28:29] op_sel_hi:[1,0]
	v_add_f32_dpp v70, v70, v70 row_ror:8 row_mask:0xf bank_mask:0xf bound_ctrl:1
	v_add_f32_dpp v72, v72, v72 row_ror:8 row_mask:0xf bank_mask:0xf bound_ctrl:1
	v_pk_mul_f32 v[82:83], v[22:23], v[28:29] op_sel_hi:[1,0]
	v_add_f32_dpp v70, v70, v70 row_ror:4 row_mask:0xf bank_mask:0xf bound_ctrl:1
	v_add_f32_dpp v72, v72, v72 row_ror:4 row_mask:0xf bank_mask:0xf bound_ctrl:1
	v_pk_mul_f32 v[116:117], v[20:21], v[28:29] op_sel:[0,1] op_sel_hi:[1,1]
	v_add_f32_dpp v70, v70, v70 row_ror:2 row_mask:0xf bank_mask:0xf bound_ctrl:1
	v_add_f32_dpp v72, v72, v72 row_ror:2 row_mask:0xf bank_mask:0xf bound_ctrl:1
	v_pk_mul_f32 v[114:115], v[22:23], v[28:29] op_sel:[0,1] op_sel_hi:[1,1]
	v_add_f32_dpp v70, v70, v70 row_ror:1 row_mask:0xf bank_mask:0xf bound_ctrl:1
	v_add_f32_dpp v72, v72, v72 row_ror:1 row_mask:0xf bank_mask:0xf bound_ctrl:1
	v_pk_fma_f32 v[38:39], v[0:1], v[8:9], v[38:39]
	v_pk_fma_f32 v[82:83], v[2:3], v[10:11], v[82:83]
	v_pk_fma_f32 v[116:117], v[4:5], v[8:9], v[116:117]
	v_pk_fma_f32 v[114:115], v[6:7], v[10:11], v[114:115]
	v_pk_fma_f32 v[0:1], v[16:17], v[70:71], v[38:39] op_sel_hi:[1,0,1]
	v_pk_fma_f32 v[2:3], v[18:19], v[70:71], v[82:83] op_sel_hi:[1,0,1]
	v_pk_fma_f32 v[4:5], v[16:17], v[72:73], v[116:117] op_sel_hi:[1,0,1]
	v_pk_fma_f32 v[6:7], v[18:19], v[72:73], v[114:115] op_sel_hi:[1,0,1]
	v_pk_mul_f32 v[110:111], v[2:3], v[26:27]
	v_pk_mul_f32 v[112:113], v[6:7], v[26:27]
	v_pk_fma_f32 v[110:111], v[0:1], v[24:25], v[110:111]
	v_pk_fma_f32 v[112:113], v[4:5], v[24:25], v[112:113]
	v_add_f32_e32 v110, v110, v111
	v_add_f32_e32 v112, v112, v113
	ds_write_b32 v119, v110 offset:28672
	ds_write_b32 v119, v112 offset:28736
	s_waitcnt lgkmcnt(2)
	v_pk_mul_f32 v[110:111], v[2:3], v[36:37]
	v_pk_mul_f32 v[112:113], v[6:7], v[36:37]
	v_pk_fma_f32 v[110:111], v[0:1], v[34:35], v[110:111]
	v_pk_fma_f32 v[112:113], v[4:5], v[34:35], v[112:113]
	v_add_f32_e32 v70, v110, v111
	v_add_f32_e32 v72, v112, v113
	v_pk_mul_f32 v[38:39], v[78:79], v[108:109] op_sel_hi:[1,0]
	v_add_f32_dpp v70, v70, v70 row_ror:8 row_mask:0xf bank_mask:0xf bound_ctrl:1
	v_add_f32_dpp v72, v72, v72 row_ror:8 row_mask:0xf bank_mask:0xf bound_ctrl:1
	v_pk_mul_f32 v[82:83], v[80:81], v[108:109] op_sel_hi:[1,0]
	v_add_f32_dpp v70, v70, v70 row_ror:4 row_mask:0xf bank_mask:0xf bound_ctrl:1
	v_add_f32_dpp v72, v72, v72 row_ror:4 row_mask:0xf bank_mask:0xf bound_ctrl:1
	v_pk_mul_f32 v[116:117], v[78:79], v[108:109] op_sel:[0,1] op_sel_hi:[1,1]
	v_add_f32_dpp v70, v70, v70 row_ror:2 row_mask:0xf bank_mask:0xf bound_ctrl:1
	v_add_f32_dpp v72, v72, v72 row_ror:2 row_mask:0xf bank_mask:0xf bound_ctrl:1
	v_pk_mul_f32 v[114:115], v[80:81], v[108:109] op_sel:[0,1] op_sel_hi:[1,1]
	v_add_f32_dpp v70, v70, v70 row_ror:1 row_mask:0xf bank_mask:0xf bound_ctrl:1
	v_add_f32_dpp v72, v72, v72 row_ror:1 row_mask:0xf bank_mask:0xf bound_ctrl:1
	v_pk_fma_f32 v[38:39], v[0:1], v[30:31], v[38:39]
	v_pk_fma_f32 v[82:83], v[2:3], v[32:33], v[82:83]
	v_pk_fma_f32 v[116:117], v[4:5], v[30:31], v[116:117]
	v_pk_fma_f32 v[114:115], v[6:7], v[32:33], v[114:115]
	v_pk_fma_f32 v[0:1], v[74:75], v[70:71], v[38:39] op_sel_hi:[1,0,1]
	v_pk_fma_f32 v[2:3], v[76:77], v[70:71], v[82:83] op_sel_hi:[1,0,1]
	v_pk_fma_f32 v[4:5], v[74:75], v[72:73], v[116:117] op_sel_hi:[1,0,1]
	v_pk_fma_f32 v[6:7], v[76:77], v[72:73], v[114:115] op_sel_hi:[1,0,1]
	v_pk_mul_f32 v[110:111], v[2:3], v[106:107]
	v_pk_mul_f32 v[112:113], v[6:7], v[106:107]
	v_pk_fma_f32 v[110:111], v[0:1], v[104:105], v[110:111]
	v_pk_fma_f32 v[112:113], v[4:5], v[104:105], v[112:113]
	v_add_f32_e32 v110, v110, v111
	v_add_f32_e32 v112, v112, v113
	ds_write_b32 v119, v110 offset:30720
	ds_write_b32 v119, v112 offset:30784
	s_setprio 0
	s_branch .LBB0_140
